# v26 plus nt streaming hint on the 96 read-once f32 X loads of the three residual GEMM epilogues
# baseline (speedup 1.0000x reference)
; __device__ __forceinline__ unsigned cvtpk(float lo, float hi) { f32x2_t v = {lo, hi}; bf16x2_t b = __builtin_convertvector(v, bf16x2_t); return __builtin_bit_cast(unsigned, b); }
;     __device__ __forceinline__ void operator()(const Acc& acc, const Unit& u, int wr, int wc, int fr, int fq) const {
;     ...
;             for (int m = 0; m < 4; ++m) { const int row = row0 + ai * HALF + m * 16; float* rp = X + (size_t)row * DM + col0; const float* ip = Xin + (size_t)row * DM + col0; bf16_t* bp = XB + (size_t)row * DM + col0; float part = 0.f;
; #pragma unroll
;                 for (int bj = 0; bj < 2; ++bj) { f32x4* p = (f32x4*)(rp + bj * HALF); const f32x4* q = (const f32x4*)(ip + bj * HALF); f32x4 a = q[0], b = q[1]; a += acc[ai][bj][m][0] * scale; b += acc[ai][bj][m][1] * scale; p[0] = a; p[1] = b;
;                     *(u32x4*)(bp + bj * HALF) = (u32x4){cvtpk(a[0], a[1]), cvtpk(a[2], a[3]), cvtpk(b[0], b[1]), cvtpk(b[2], b[3])};
;                     part += (a[0] * a[0] + a[1] * a[1]) + (a[2] * a[2] + a[3] * a[3]) + (b[0] * b[0] + b[1] * b[1]) + (b[2] * b[2] + b[3] * b[3]); }
;                 part += __shfl_xor(part, 16); part += __shfl_xor(part, 32);
;                 if (fq == 0) __hip_atomic_fetch_add(SS + row, (u64)(part * SSF), __ATOMIC_RELAXED, __HIP_MEMORY_SCOPE_AGENT); }
.LBB0_173:
	v_lshl_add_u32 v140, s66, 8, v144
	v_lshl_or_b32 v138, s67, 8, v146
	v_ashrrev_i32_e32 v141, 31, v140
	v_ashrrev_i32_e32 v139, 31, v138
	v_lshlrev_b64 v[156:157], 12, v[140:141]
	v_lshlrev_b64 v[142:143], 2, v[138:139]
	v_lshl_add_u64 v[148:149], s[2:3], 0, v[156:157]
	v_lshl_add_u64 v[158:159], v[148:149], 0, v[142:143]
	global_load_dwordx4 v[148:151], v[158:159], off nt
	global_load_dwordx4 v[152:155], v[158:159], off offset:16 nt
	v_lshlrev_b64 v[162:163], 11, v[140:141]
	v_lshl_add_u64 v[156:157], s[48:49], 0, v[156:157]
	v_lshl_add_u64 v[162:163], s[20:21], 0, v[162:163]
	v_lshl_add_u64 v[164:165], v[156:157], 0, v[142:143]
	v_lshl_add_u64 v[162:163], v[138:139], 1, v[162:163]
	s_waitcnt vmcnt(0)
	v_pk_fma_f32 v[126:127], v[126:127], 0.5, v[150:151] op_sel_hi:[1,0,1]
	v_pk_fma_f32 v[124:125], v[124:125], 0.5, v[148:149] op_sel_hi:[1,0,1]
	v_pk_fma_f32 v[150:151], v[122:123], 0.5, v[154:155] op_sel_hi:[1,0,1]
	v_pk_fma_f32 v[148:149], v[120:121], 0.5, v[152:153] op_sel_hi:[1,0,1]
	v_cvt_pk_bf16_f32 v120, v124, v125
	v_cvt_pk_bf16_f32 v121, v126, v127
	v_cvt_pk_bf16_f32 v122, v148, v149
	v_cvt_pk_bf16_f32 v123, v150, v151
	global_store_dwordx4 v[164:165], v[124:127], off
	global_store_dwordx4 v[164:165], v[148:151], off offset:16
	global_store_dwordx4 v[162:163], v[120:123], off
	global_load_dwordx4 v[152:155], v[158:159], off offset:512 nt
	s_nop 0
	global_load_dwordx4 v[156:159], v[158:159], off offset:528 nt
	v_and_b32_e32 v121, 64, v229
	v_xor_b32_e32 v120, 16, v229
	v_add_u32_e32 v121, 64, v121
	v_xor_b32_e32 v122, 32, v229
	v_cmp_lt_i32_e32 vcc, v120, v121
	v_mul_f32_e32 v123, v127, v127
	v_fmac_f32_e32 v123, v126, v126
	v_cndmask_b32_e32 v120, v229, v120, vcc
	v_cmp_lt_i32_e32 vcc, v122, v121
	v_lshlrev_b32_e32 v121, 2, v120
	v_mul_f32_e32 v127, v151, v151
	v_cndmask_b32_e32 v122, v229, v122, vcc
	v_lshlrev_b32_e32 v120, 2, v122
	v_mul_f32_e32 v122, v125, v125
	v_mul_f32_e32 v125, v149, v149
	v_fmac_f32_e32 v122, v124, v124
	v_fmac_f32_e32 v125, v148, v148
	v_add_f32_e32 v122, v122, v123
	v_fmac_f32_e32 v127, v150, v150
	v_add_f32_e32 v122, v125, v122
	v_add_f32_e32 v126, v127, v122
	s_waitcnt vmcnt(1)
	v_pk_fma_f32 v[118:119], v[118:119], 0.5, v[154:155] op_sel_hi:[1,0,1]
	v_pk_fma_f32 v[116:117], v[116:117], 0.5, v[152:153] op_sel_hi:[1,0,1]
	s_waitcnt vmcnt(0)
	v_pk_fma_f32 v[122:123], v[112:113], 0.5, v[156:157] op_sel_hi:[1,0,1]
	v_mul_f32_e32 v112, v117, v117
	v_mul_f32_e32 v113, v119, v119
	v_pk_fma_f32 v[124:125], v[114:115], 0.5, v[158:159] op_sel_hi:[1,0,1]
	v_mul_f32_e32 v114, v123, v123
	v_fmac_f32_e32 v112, v116, v116
	v_fmac_f32_e32 v113, v118, v118
	v_mul_f32_e32 v115, v125, v125
	v_fmac_f32_e32 v114, v122, v122
	v_add_f32_e32 v112, v112, v113
	v_add_f32_e32 v112, v114, v112
	v_fmac_f32_e32 v115, v124, v124
	v_add_f32_e32 v112, v115, v112
	v_add_f32_e32 v112, v126, v112
	ds_bpermute_b32 v113, v121, v112
	global_store_dwordx4 v[164:165], v[116:119], off offset:512
	global_store_dwordx4 v[164:165], v[122:125], off offset:528
	s_waitcnt lgkmcnt(0)
	v_add_f32_e32 v114, v112, v113
	ds_bpermute_b32 v115, v120, v114
	v_cvt_pk_bf16_f32 v116, v116, v117
	v_cvt_pk_bf16_f32 v117, v118, v119
	v_cvt_pk_bf16_f32 v118, v122, v123
	v_cvt_pk_bf16_f32 v119, v124, v125
	v_lshl_add_u64 v[112:113], v[140:141], 3, s[18:19]
	global_store_dwordx4 v[162:163], v[116:119], off offset:256
	s_and_saveexec_b64 s[16:17], s[42:43]
	s_cbranch_execz .LBB0_175
	s_waitcnt lgkmcnt(0)
	v_add_f32_e32 v114, v114, v115
	v_mul_f32_e32 v114, 0x4b800000, v114
	v_trunc_f32_e32 v114, v114
	v_mul_f32_e32 v115, 0x2f800000, v114
	v_floor_f32_e32 v115, v115
	v_fmac_f32_e32 v114, 0xcf800000, v115
	v_cvt_u32_f32_e32 v114, v114
	v_cvt_u32_f32_e32 v115, v115
	global_atomic_add_x2 v[112:113], v[114:115], off
.LBB0_175:
	s_or_b64 exec, exec, s[16:17]
	v_or_b32_e32 v118, 16, v140
	v_ashrrev_i32_e32 v119, 31, v118
	v_lshlrev_b64 v[126:127], 12, v[118:119]
	s_waitcnt lgkmcnt(0)
	v_lshl_add_u64 v[114:115], s[2:3], 0, v[126:127]
	v_lshl_add_u64 v[148:149], v[114:115], 0, v[142:143]
	global_load_dwordx4 v[114:117], v[148:149], off nt
	global_load_dwordx4 v[122:125], v[148:149], off offset:16 nt
	v_lshlrev_b64 v[118:119], 11, v[118:119]
	v_lshl_add_u64 v[126:127], s[48:49], 0, v[126:127]
	v_lshl_add_u64 v[118:119], s[20:21], 0, v[118:119]
	v_lshl_add_u64 v[126:127], v[126:127], 0, v[142:143]
	v_lshl_add_u64 v[118:119], v[138:139], 1, v[118:119]
	s_waitcnt vmcnt(1)
	v_pk_fma_f32 v[110:111], v[110:111], 0.5, v[116:117] op_sel_hi:[1,0,1]
	v_pk_fma_f32 v[108:109], v[108:109], 0.5, v[114:115] op_sel_hi:[1,0,1]
	s_waitcnt vmcnt(0)
	v_pk_fma_f32 v[106:107], v[106:107], 0.5, v[124:125] op_sel_hi:[1,0,1]
	v_pk_fma_f32 v[104:105], v[104:105], 0.5, v[122:123] op_sel_hi:[1,0,1]
	v_cvt_pk_bf16_f32 v114, v108, v109
	v_cvt_pk_bf16_f32 v115, v110, v111
	v_cvt_pk_bf16_f32 v116, v104, v105
	v_cvt_pk_bf16_f32 v117, v106, v107
	global_store_dwordx4 v[126:127], v[108:111], off
	global_store_dwordx4 v[126:127], v[104:107], off offset:16
	global_store_dwordx4 v[118:119], v[114:117], off
	global_load_dwordx4 v[114:117], v[148:149], off offset:512 nt
	s_nop 0
	global_load_dwordx4 v[122:125], v[148:149], off offset:528 nt
	v_mul_f32_e32 v109, v109, v109
	v_mul_f32_e32 v111, v111, v111
	v_mul_f32_e32 v105, v105, v105
	v_fmac_f32_e32 v109, v108, v108
	v_fmac_f32_e32 v111, v110, v110
	v_mul_f32_e32 v107, v107, v107
	v_fmac_f32_e32 v105, v104, v104
	v_add_f32_e32 v104, v109, v111
	v_fmac_f32_e32 v107, v106, v106
	v_add_f32_e32 v104, v105, v104
	v_add_f32_e32 v108, v107, v104
	s_waitcnt vmcnt(1)
	v_pk_fma_f32 v[102:103], v[102:103], 0.5, v[116:117] op_sel_hi:[1,0,1]
	v_pk_fma_f32 v[100:101], v[100:101], 0.5, v[114:115] op_sel_hi:[1,0,1]
	s_waitcnt vmcnt(0)
	v_pk_fma_f32 v[104:105], v[96:97], 0.5, v[122:123] op_sel_hi:[1,0,1]
	v_mul_f32_e32 v96, v101, v101
	v_mul_f32_e32 v97, v103, v103
	v_pk_fma_f32 v[106:107], v[98:99], 0.5, v[124:125] op_sel_hi:[1,0,1]
	v_mul_f32_e32 v98, v105, v105
	v_fmac_f32_e32 v96, v100, v100
	v_fmac_f32_e32 v97, v102, v102
	v_mul_f32_e32 v99, v107, v107
	v_fmac_f32_e32 v98, v104, v104
	v_add_f32_e32 v96, v96, v97
	v_add_f32_e32 v96, v98, v96
	v_fmac_f32_e32 v99, v106, v106
	v_add_f32_e32 v96, v99, v96
	v_add_f32_e32 v96, v108, v96
	ds_bpermute_b32 v97, v121, v96
	global_store_dwordx4 v[126:127], v[100:103], off offset:512
	global_store_dwordx4 v[126:127], v[104:107], off offset:528
	v_cvt_pk_bf16_f32 v98, v100, v101
	v_cvt_pk_bf16_f32 v99, v102, v103
	v_cvt_pk_bf16_f32 v100, v104, v105
	s_waitcnt lgkmcnt(0)
	v_add_f32_e32 v96, v96, v97
	ds_bpermute_b32 v97, v120, v96
	v_cvt_pk_bf16_f32 v101, v106, v107
	global_store_dwordx4 v[118:119], v[98:101], off offset:256
	s_and_saveexec_b64 s[16:17], s[42:43]
	s_cbranch_execz .LBB0_177
	s_waitcnt lgkmcnt(0)
	v_add_f32_e32 v96, v96, v97
	v_mul_f32_e32 v96, 0x4b800000, v96
	v_trunc_f32_e32 v96, v96
	v_mul_f32_e32 v97, 0x2f800000, v96
	v_floor_f32_e32 v97, v97
	v_fmac_f32_e32 v96, 0xcf800000, v97
	v_cvt_u32_f32_e32 v96, v96
	v_cvt_u32_f32_e32 v97, v97
	global_atomic_add_x2 v[112:113], v[96:97], off offset:128
; __device__ __forceinline__ unsigned cvtpk(float lo, float hi) { f32x2_t v = {lo, hi}; bf16x2_t b = __builtin_convertvector(v, bf16x2_t); return __builtin_bit_cast(unsigned, b); }
;     __device__ __forceinline__ void operator()(const Acc& acc, const Unit& u, int wr, int wc, int fr, int fq) const {
;     ...
;             for (int m = 0; m < 4; ++m) { const int row = row0 + ai * HALF + m * 16; float* rp = X + (size_t)row * DM + col0; const float* ip = Xin + (size_t)row * DM + col0; bf16_t* bp = XB + (size_t)row * DM + col0; float part = 0.f;
; #pragma unroll
;                 for (int bj = 0; bj < 2; ++bj) { f32x4* p = (f32x4*)(rp + bj * HALF); const f32x4* q = (const f32x4*)(ip + bj * HALF); f32x4 a = q[0], b = q[1]; a += acc[ai][bj][m][0] * scale; b += acc[ai][bj][m][1] * scale; p[0] = a; p[1] = b;
;                     *(u32x4*)(bp + bj * HALF) = (u32x4){cvtpk(a[0], a[1]), cvtpk(a[2], a[3]), cvtpk(b[0], b[1]), cvtpk(b[2], b[3])};
;                     part += (a[0] * a[0] + a[1] * a[1]) + (a[2] * a[2] + a[3] * a[3]) + (b[0] * b[0] + b[1] * b[1]) + (b[2] * b[2] + b[3] * b[3]); }
;                 part += __shfl_xor(part, 16); part += __shfl_xor(part, 32);
;                 if (fq == 0) __hip_atomic_fetch_add(SS + row, (u64)(part * SSF), __ATOMIC_RELAXED, __HIP_MEMORY_SCOPE_AGENT); }
.LBB0_177:
	s_or_b64 exec, exec, s[16:17]
	v_or_b32_e32 v104, 32, v140
	v_ashrrev_i32_e32 v105, 31, v104
	v_lshlrev_b64 v[106:107], 12, v[104:105]
	s_waitcnt lgkmcnt(0)
	v_lshl_add_u64 v[96:97], s[2:3], 0, v[106:107]
	v_lshl_add_u64 v[108:109], v[96:97], 0, v[142:143]
	global_load_dwordx4 v[96:99], v[108:109], off nt
	global_load_dwordx4 v[100:103], v[108:109], off offset:16 nt
	v_lshlrev_b64 v[104:105], 11, v[104:105]
	v_lshl_add_u64 v[106:107], s[48:49], 0, v[106:107]
	v_lshl_add_u64 v[104:105], s[20:21], 0, v[104:105]
	v_lshl_add_u64 v[106:107], v[106:107], 0, v[142:143]
	v_lshl_add_u64 v[104:105], v[138:139], 1, v[104:105]
	s_waitcnt vmcnt(1)
	v_pk_fma_f32 v[94:95], v[94:95], 0.5, v[98:99] op_sel_hi:[1,0,1]
	v_pk_fma_f32 v[92:93], v[92:93], 0.5, v[96:97] op_sel_hi:[1,0,1]
	s_waitcnt vmcnt(0)
	v_pk_fma_f32 v[90:91], v[90:91], 0.5, v[102:103] op_sel_hi:[1,0,1]
	v_pk_fma_f32 v[88:89], v[88:89], 0.5, v[100:101] op_sel_hi:[1,0,1]
	v_cvt_pk_bf16_f32 v96, v92, v93
	v_cvt_pk_bf16_f32 v97, v94, v95
	v_cvt_pk_bf16_f32 v98, v88, v89
	v_cvt_pk_bf16_f32 v99, v90, v91
	global_store_dwordx4 v[106:107], v[92:95], off
	global_store_dwordx4 v[106:107], v[88:91], off offset:16
	global_store_dwordx4 v[104:105], v[96:99], off
	global_load_dwordx4 v[96:99], v[108:109], off offset:512 nt
	s_nop 0
	global_load_dwordx4 v[100:103], v[108:109], off offset:528 nt
	v_mul_f32_e32 v93, v93, v93
	v_mul_f32_e32 v95, v95, v95
	v_mul_f32_e32 v89, v89, v89
	v_fmac_f32_e32 v93, v92, v92
	v_fmac_f32_e32 v95, v94, v94
	v_mul_f32_e32 v91, v91, v91
	v_fmac_f32_e32 v89, v88, v88
	v_add_f32_e32 v88, v93, v95
	v_fmac_f32_e32 v91, v90, v90
	v_add_f32_e32 v88, v89, v88
	v_add_f32_e32 v92, v91, v88
	s_waitcnt vmcnt(1)
	v_pk_fma_f32 v[86:87], v[86:87], 0.5, v[98:99] op_sel_hi:[1,0,1]
	v_pk_fma_f32 v[84:85], v[84:85], 0.5, v[96:97] op_sel_hi:[1,0,1]
	s_waitcnt vmcnt(0)
	v_pk_fma_f32 v[88:89], v[80:81], 0.5, v[100:101] op_sel_hi:[1,0,1]
	v_mul_f32_e32 v80, v85, v85
	v_mul_f32_e32 v81, v87, v87
	v_pk_fma_f32 v[90:91], v[82:83], 0.5, v[102:103] op_sel_hi:[1,0,1]
	v_mul_f32_e32 v82, v89, v89
	v_fmac_f32_e32 v80, v84, v84
	v_fmac_f32_e32 v81, v86, v86
	v_mul_f32_e32 v83, v91, v91
	v_fmac_f32_e32 v82, v88, v88
	v_add_f32_e32 v80, v80, v81
	v_add_f32_e32 v80, v82, v80
	v_fmac_f32_e32 v83, v90, v90
	v_add_f32_e32 v80, v83, v80
	v_add_f32_e32 v80, v92, v80
	ds_bpermute_b32 v81, v121, v80
	global_store_dwordx4 v[106:107], v[84:87], off offset:512
	global_store_dwordx4 v[106:107], v[88:91], off offset:528
	v_cvt_pk_bf16_f32 v82, v84, v85
	v_cvt_pk_bf16_f32 v83, v86, v87
	v_cvt_pk_bf16_f32 v84, v88, v89
	s_waitcnt lgkmcnt(0)
	v_add_f32_e32 v80, v80, v81
	ds_bpermute_b32 v81, v120, v80
	v_cvt_pk_bf16_f32 v85, v90, v91
	global_store_dwordx4 v[104:105], v[82:85], off offset:256
	s_and_saveexec_b64 s[16:17], s[42:43]
	s_cbranch_execz .LBB0_179
	s_waitcnt lgkmcnt(0)
	v_add_f32_e32 v80, v80, v81
	v_mul_f32_e32 v80, 0x4b800000, v80
	v_trunc_f32_e32 v80, v80
	v_mul_f32_e32 v81, 0x2f800000, v80
	v_floor_f32_e32 v81, v81
	v_fmac_f32_e32 v80, 0xcf800000, v81
	v_cvt_u32_f32_e32 v80, v80
	v_cvt_u32_f32_e32 v81, v81
	global_atomic_add_x2 v[112:113], v[80:81], off offset:256
.LBB0_179:
	s_or_b64 exec, exec, s[16:17]
	v_or_b32_e32 v88, 48, v140
	v_ashrrev_i32_e32 v89, 31, v88
	v_lshlrev_b64 v[90:91], 12, v[88:89]
	s_waitcnt lgkmcnt(0)
	v_lshl_add_u64 v[80:81], s[2:3], 0, v[90:91]
	v_lshl_add_u64 v[92:93], v[80:81], 0, v[142:143]
	global_load_dwordx4 v[80:83], v[92:93], off nt
	global_load_dwordx4 v[84:87], v[92:93], off offset:16 nt
	v_lshlrev_b64 v[88:89], 11, v[88:89]
	v_lshl_add_u64 v[90:91], s[48:49], 0, v[90:91]
	v_lshl_add_u64 v[88:89], s[20:21], 0, v[88:89]
	v_lshl_add_u64 v[90:91], v[90:91], 0, v[142:143]
	v_lshl_add_u64 v[88:89], v[138:139], 1, v[88:89]
	s_waitcnt vmcnt(1)
	v_pk_fma_f32 v[78:79], v[78:79], 0.5, v[82:83] op_sel_hi:[1,0,1]
	v_pk_fma_f32 v[76:77], v[76:77], 0.5, v[80:81] op_sel_hi:[1,0,1]
	s_waitcnt vmcnt(0)
	v_pk_fma_f32 v[74:75], v[74:75], 0.5, v[86:87] op_sel_hi:[1,0,1]
	v_pk_fma_f32 v[72:73], v[72:73], 0.5, v[84:85] op_sel_hi:[1,0,1]
	v_cvt_pk_bf16_f32 v80, v76, v77
	v_cvt_pk_bf16_f32 v81, v78, v79
	v_cvt_pk_bf16_f32 v82, v72, v73
	v_cvt_pk_bf16_f32 v83, v74, v75
	global_store_dwordx4 v[90:91], v[76:79], off
	global_store_dwordx4 v[90:91], v[72:75], off offset:16
	global_store_dwordx4 v[88:89], v[80:83], off
	global_load_dwordx4 v[80:83], v[92:93], off offset:512 nt
	s_nop 0
	global_load_dwordx4 v[84:87], v[92:93], off offset:528 nt
	v_mul_f32_e32 v77, v77, v77
	v_mul_f32_e32 v79, v79, v79
	v_mul_f32_e32 v73, v73, v73
	v_fmac_f32_e32 v77, v76, v76
	v_fmac_f32_e32 v79, v78, v78
	v_mul_f32_e32 v75, v75, v75
	v_fmac_f32_e32 v73, v72, v72
	v_add_f32_e32 v72, v77, v79
	v_fmac_f32_e32 v75, v74, v74
	v_add_f32_e32 v72, v73, v72
	v_add_f32_e32 v76, v75, v72
	s_waitcnt vmcnt(1)
	v_pk_fma_f32 v[70:71], v[70:71], 0.5, v[82:83] op_sel_hi:[1,0,1]
	v_pk_fma_f32 v[68:69], v[68:69], 0.5, v[80:81] op_sel_hi:[1,0,1]
	s_waitcnt vmcnt(0)
	v_pk_fma_f32 v[72:73], v[64:65], 0.5, v[84:85] op_sel_hi:[1,0,1]
	v_mul_f32_e32 v64, v69, v69
	v_mul_f32_e32 v65, v71, v71
	v_pk_fma_f32 v[74:75], v[66:67], 0.5, v[86:87] op_sel_hi:[1,0,1]
	v_mul_f32_e32 v66, v73, v73
	v_fmac_f32_e32 v64, v68, v68
	v_fmac_f32_e32 v65, v70, v70
	v_mul_f32_e32 v67, v75, v75
	v_fmac_f32_e32 v66, v72, v72
	v_add_f32_e32 v64, v64, v65
	v_add_f32_e32 v64, v66, v64
	v_fmac_f32_e32 v67, v74, v74
	v_add_f32_e32 v64, v67, v64
	v_add_f32_e32 v64, v76, v64
	ds_bpermute_b32 v65, v121, v64
	global_store_dwordx4 v[90:91], v[68:71], off offset:512
	global_store_dwordx4 v[90:91], v[72:75], off offset:528
	v_cvt_pk_bf16_f32 v66, v68, v69
	v_cvt_pk_bf16_f32 v67, v70, v71
	v_cvt_pk_bf16_f32 v68, v72, v73
	s_waitcnt lgkmcnt(0)
	v_add_f32_e32 v64, v64, v65
	ds_bpermute_b32 v65, v120, v64
	v_cvt_pk_bf16_f32 v69, v74, v75
	global_store_dwordx4 v[88:89], v[66:69], off offset:256
	s_and_saveexec_b64 s[16:17], s[42:43]
	s_cbranch_execz .LBB0_181
	s_waitcnt lgkmcnt(0)
	v_add_f32_e32 v64, v64, v65
	v_mul_f32_e32 v64, 0x4b800000, v64
	v_trunc_f32_e32 v64, v64
	v_mul_f32_e32 v65, 0x2f800000, v64
	v_floor_f32_e32 v65, v65
	v_fmac_f32_e32 v64, 0xcf800000, v65
	v_cvt_u32_f32_e32 v64, v64
	v_cvt_u32_f32_e32 v65, v65
	global_atomic_add_x2 v[112:113], v[64:65], off offset:384
; __device__ __forceinline__ unsigned cvtpk(float lo, float hi) { f32x2_t v = {lo, hi}; bf16x2_t b = __builtin_convertvector(v, bf16x2_t); return __builtin_bit_cast(unsigned, b); }
;     __device__ __forceinline__ void operator()(const Acc& acc, const Unit& u, int wr, int wc, int fr, int fq) const {
;     ...
;             for (int m = 0; m < 4; ++m) { const int row = row0 + ai * HALF + m * 16; float* rp = X + (size_t)row * DM + col0; const float* ip = Xin + (size_t)row * DM + col0; bf16_t* bp = XB + (size_t)row * DM + col0; float part = 0.f;
; #pragma unroll
;                 for (int bj = 0; bj < 2; ++bj) { f32x4* p = (f32x4*)(rp + bj * HALF); const f32x4* q = (const f32x4*)(ip + bj * HALF); f32x4 a = q[0], b = q[1]; a += acc[ai][bj][m][0] * scale; b += acc[ai][bj][m][1] * scale; p[0] = a; p[1] = b;
;                     *(u32x4*)(bp + bj * HALF) = (u32x4){cvtpk(a[0], a[1]), cvtpk(a[2], a[3]), cvtpk(b[0], b[1]), cvtpk(b[2], b[3])};
;                     part += (a[0] * a[0] + a[1] * a[1]) + (a[2] * a[2] + a[3] * a[3]) + (b[0] * b[0] + b[1] * b[1]) + (b[2] * b[2] + b[3] * b[3]); }
;                 part += __shfl_xor(part, 16); part += __shfl_xor(part, 32);
;                 if (fq == 0) __hip_atomic_fetch_add(SS + row, (u64)(part * SSF), __ATOMIC_RELAXED, __HIP_MEMORY_SCOPE_AGENT); }
.LBB0_181:
	s_or_b64 exec, exec, s[16:17]
	v_add_u32_e32 v72, 0x80, v140
	v_ashrrev_i32_e32 v73, 31, v72
	v_lshlrev_b64 v[74:75], 12, v[72:73]
	s_waitcnt lgkmcnt(0)
	v_lshl_add_u64 v[64:65], s[2:3], 0, v[74:75]
	v_lshl_add_u64 v[76:77], v[64:65], 0, v[142:143]
	global_load_dwordx4 v[64:67], v[76:77], off nt
	global_load_dwordx4 v[68:71], v[76:77], off offset:16 nt
	v_lshlrev_b64 v[72:73], 11, v[72:73]
	v_lshl_add_u64 v[74:75], s[48:49], 0, v[74:75]
	v_lshl_add_u64 v[72:73], s[20:21], 0, v[72:73]
	v_lshl_add_u64 v[74:75], v[74:75], 0, v[142:143]
	v_lshl_add_u64 v[72:73], v[138:139], 1, v[72:73]
	s_waitcnt vmcnt(1)
	v_pk_fma_f32 v[62:63], v[62:63], 0.5, v[66:67] op_sel_hi:[1,0,1]
	v_pk_fma_f32 v[60:61], v[60:61], 0.5, v[64:65] op_sel_hi:[1,0,1]
	s_waitcnt vmcnt(0)
	v_pk_fma_f32 v[58:59], v[58:59], 0.5, v[70:71] op_sel_hi:[1,0,1]
	v_pk_fma_f32 v[56:57], v[56:57], 0.5, v[68:69] op_sel_hi:[1,0,1]
	v_cvt_pk_bf16_f32 v64, v60, v61
	v_cvt_pk_bf16_f32 v65, v62, v63
	v_cvt_pk_bf16_f32 v66, v56, v57
	v_cvt_pk_bf16_f32 v67, v58, v59
	global_store_dwordx4 v[74:75], v[60:63], off
	global_store_dwordx4 v[74:75], v[56:59], off offset:16
	global_store_dwordx4 v[72:73], v[64:67], off
	global_load_dwordx4 v[64:67], v[76:77], off offset:512 nt
	s_nop 0
	global_load_dwordx4 v[68:71], v[76:77], off offset:528 nt
	v_mul_f32_e32 v61, v61, v61
	v_mul_f32_e32 v63, v63, v63
	v_mul_f32_e32 v57, v57, v57
	v_fmac_f32_e32 v61, v60, v60
	v_fmac_f32_e32 v63, v62, v62
	v_mul_f32_e32 v59, v59, v59
	v_fmac_f32_e32 v57, v56, v56
	v_add_f32_e32 v56, v61, v63
	v_fmac_f32_e32 v59, v58, v58
	v_add_f32_e32 v56, v57, v56
	v_add_f32_e32 v60, v59, v56
	s_waitcnt vmcnt(1)
	v_pk_fma_f32 v[54:55], v[54:55], 0.5, v[66:67] op_sel_hi:[1,0,1]
	v_pk_fma_f32 v[52:53], v[52:53], 0.5, v[64:65] op_sel_hi:[1,0,1]
	s_waitcnt vmcnt(0)
	v_pk_fma_f32 v[56:57], v[48:49], 0.5, v[68:69] op_sel_hi:[1,0,1]
	v_mul_f32_e32 v48, v53, v53
	v_mul_f32_e32 v49, v55, v55
	v_pk_fma_f32 v[58:59], v[50:51], 0.5, v[70:71] op_sel_hi:[1,0,1]
	v_mul_f32_e32 v50, v57, v57
	v_fmac_f32_e32 v48, v52, v52
	v_fmac_f32_e32 v49, v54, v54
	v_mul_f32_e32 v51, v59, v59
	v_fmac_f32_e32 v50, v56, v56
	v_add_f32_e32 v48, v48, v49
	v_add_f32_e32 v48, v50, v48
	v_fmac_f32_e32 v51, v58, v58
	v_add_f32_e32 v48, v51, v48
	v_add_f32_e32 v48, v60, v48
	ds_bpermute_b32 v49, v121, v48
	global_store_dwordx4 v[74:75], v[52:55], off offset:512
	global_store_dwordx4 v[74:75], v[56:59], off offset:528
	v_cvt_pk_bf16_f32 v50, v52, v53
	v_cvt_pk_bf16_f32 v51, v54, v55
	v_cvt_pk_bf16_f32 v52, v56, v57
	s_waitcnt lgkmcnt(0)
	v_add_f32_e32 v48, v48, v49
	ds_bpermute_b32 v49, v120, v48
	v_cvt_pk_bf16_f32 v53, v58, v59
	global_store_dwordx4 v[72:73], v[50:53], off offset:256
	s_and_saveexec_b64 s[16:17], s[42:43]
	s_cbranch_execz .LBB0_183
	s_waitcnt lgkmcnt(0)
	v_add_f32_e32 v48, v48, v49
	v_mul_f32_e32 v48, 0x4b800000, v48
	v_trunc_f32_e32 v48, v48
	v_mul_f32_e32 v49, 0x2f800000, v48
	v_floor_f32_e32 v49, v49
	v_fmac_f32_e32 v48, 0xcf800000, v49
	v_cvt_u32_f32_e32 v48, v48
	v_cvt_u32_f32_e32 v49, v49
	global_atomic_add_x2 v[112:113], v[48:49], off offset:1024
.LBB0_183:
	s_or_b64 exec, exec, s[16:17]
	v_add_u32_e32 v56, 0x90, v140
	v_ashrrev_i32_e32 v57, 31, v56
	v_lshlrev_b64 v[58:59], 12, v[56:57]
	s_waitcnt lgkmcnt(0)
	v_lshl_add_u64 v[48:49], s[2:3], 0, v[58:59]
	v_lshl_add_u64 v[60:61], v[48:49], 0, v[142:143]
	global_load_dwordx4 v[48:51], v[60:61], off nt
	global_load_dwordx4 v[52:55], v[60:61], off offset:16 nt
	v_lshlrev_b64 v[56:57], 11, v[56:57]
	v_lshl_add_u64 v[58:59], s[48:49], 0, v[58:59]
	v_lshl_add_u64 v[56:57], s[20:21], 0, v[56:57]
	v_lshl_add_u64 v[58:59], v[58:59], 0, v[142:143]
	v_lshl_add_u64 v[56:57], v[138:139], 1, v[56:57]
	s_waitcnt vmcnt(1)
	v_pk_fma_f32 v[46:47], v[46:47], 0.5, v[50:51] op_sel_hi:[1,0,1]
	v_pk_fma_f32 v[44:45], v[44:45], 0.5, v[48:49] op_sel_hi:[1,0,1]
	s_waitcnt vmcnt(0)
	v_pk_fma_f32 v[42:43], v[42:43], 0.5, v[54:55] op_sel_hi:[1,0,1]
	v_pk_fma_f32 v[40:41], v[40:41], 0.5, v[52:53] op_sel_hi:[1,0,1]
	v_cvt_pk_bf16_f32 v48, v44, v45
	v_cvt_pk_bf16_f32 v49, v46, v47
	v_cvt_pk_bf16_f32 v50, v40, v41
	v_cvt_pk_bf16_f32 v51, v42, v43
	global_store_dwordx4 v[58:59], v[44:47], off
	global_store_dwordx4 v[58:59], v[40:43], off offset:16
	global_store_dwordx4 v[56:57], v[48:51], off
	global_load_dwordx4 v[48:51], v[60:61], off offset:512 nt
	s_nop 0
	global_load_dwordx4 v[52:55], v[60:61], off offset:528 nt
	v_mul_f32_e32 v45, v45, v45
	v_mul_f32_e32 v47, v47, v47
	v_mul_f32_e32 v41, v41, v41
	v_fmac_f32_e32 v45, v44, v44
	v_fmac_f32_e32 v47, v46, v46
	v_mul_f32_e32 v43, v43, v43
	v_fmac_f32_e32 v41, v40, v40
	v_add_f32_e32 v40, v45, v47
	v_fmac_f32_e32 v43, v42, v42
	v_add_f32_e32 v40, v41, v40
	v_add_f32_e32 v44, v43, v40
	s_waitcnt vmcnt(1)
	v_pk_fma_f32 v[38:39], v[38:39], 0.5, v[50:51] op_sel_hi:[1,0,1]
	v_pk_fma_f32 v[36:37], v[36:37], 0.5, v[48:49] op_sel_hi:[1,0,1]
	s_waitcnt vmcnt(0)
	v_pk_fma_f32 v[40:41], v[32:33], 0.5, v[52:53] op_sel_hi:[1,0,1]
	v_mul_f32_e32 v32, v37, v37
	v_mul_f32_e32 v33, v39, v39
	v_pk_fma_f32 v[42:43], v[34:35], 0.5, v[54:55] op_sel_hi:[1,0,1]
	v_mul_f32_e32 v34, v41, v41
	v_fmac_f32_e32 v32, v36, v36
	v_fmac_f32_e32 v33, v38, v38
	v_mul_f32_e32 v35, v43, v43
	v_fmac_f32_e32 v34, v40, v40
	v_add_f32_e32 v32, v32, v33
	v_add_f32_e32 v32, v34, v32
	v_fmac_f32_e32 v35, v42, v42
	v_add_f32_e32 v32, v35, v32
	v_add_f32_e32 v32, v44, v32
	ds_bpermute_b32 v33, v121, v32
	global_store_dwordx4 v[58:59], v[36:39], off offset:512
	global_store_dwordx4 v[58:59], v[40:43], off offset:528
	v_cvt_pk_bf16_f32 v34, v36, v37
	v_cvt_pk_bf16_f32 v35, v38, v39
	v_cvt_pk_bf16_f32 v36, v40, v41
	s_waitcnt lgkmcnt(0)
	v_add_f32_e32 v32, v32, v33
	ds_bpermute_b32 v33, v120, v32
	v_cvt_pk_bf16_f32 v37, v42, v43
	global_store_dwordx4 v[56:57], v[34:37], off offset:256
	s_and_saveexec_b64 s[16:17], s[42:43]
	s_cbranch_execz .LBB0_185
	s_waitcnt lgkmcnt(0)
	v_add_f32_e32 v32, v32, v33
	v_mul_f32_e32 v32, 0x4b800000, v32
	v_trunc_f32_e32 v32, v32
	v_mul_f32_e32 v33, 0x2f800000, v32
	v_floor_f32_e32 v33, v33
	v_fmac_f32_e32 v32, 0xcf800000, v33
	v_cvt_u32_f32_e32 v32, v32
	v_cvt_u32_f32_e32 v33, v33
	global_atomic_add_x2 v[112:113], v[32:33], off offset:1152
; __device__ __forceinline__ unsigned cvtpk(float lo, float hi) { f32x2_t v = {lo, hi}; bf16x2_t b = __builtin_convertvector(v, bf16x2_t); return __builtin_bit_cast(unsigned, b); }
;     __device__ __forceinline__ void operator()(const Acc& acc, const Unit& u, int wr, int wc, int fr, int fq) const {
;     ...
;             for (int m = 0; m < 4; ++m) { const int row = row0 + ai * HALF + m * 16; float* rp = X + (size_t)row * DM + col0; const float* ip = Xin + (size_t)row * DM + col0; bf16_t* bp = XB + (size_t)row * DM + col0; float part = 0.f;
; #pragma unroll
;                 for (int bj = 0; bj < 2; ++bj) { f32x4* p = (f32x4*)(rp + bj * HALF); const f32x4* q = (const f32x4*)(ip + bj * HALF); f32x4 a = q[0], b = q[1]; a += acc[ai][bj][m][0] * scale; b += acc[ai][bj][m][1] * scale; p[0] = a; p[1] = b;
;                     *(u32x4*)(bp + bj * HALF) = (u32x4){cvtpk(a[0], a[1]), cvtpk(a[2], a[3]), cvtpk(b[0], b[1]), cvtpk(b[2], b[3])};
;                     part += (a[0] * a[0] + a[1] * a[1]) + (a[2] * a[2] + a[3] * a[3]) + (b[0] * b[0] + b[1] * b[1]) + (b[2] * b[2] + b[3] * b[3]); }
;                 part += __shfl_xor(part, 16); part += __shfl_xor(part, 32);
;                 if (fq == 0) __hip_atomic_fetch_add(SS + row, (u64)(part * SSF), __ATOMIC_RELAXED, __HIP_MEMORY_SCOPE_AGENT); }
.LBB0_185:
	s_or_b64 exec, exec, s[16:17]
	v_add_u32_e32 v40, 0xa0, v140
	v_ashrrev_i32_e32 v41, 31, v40
	v_lshlrev_b64 v[42:43], 12, v[40:41]
	s_waitcnt lgkmcnt(0)
	v_lshl_add_u64 v[32:33], s[2:3], 0, v[42:43]
	v_lshl_add_u64 v[44:45], v[32:33], 0, v[142:143]
	global_load_dwordx4 v[32:35], v[44:45], off nt
	global_load_dwordx4 v[36:39], v[44:45], off offset:16 nt
	v_lshlrev_b64 v[40:41], 11, v[40:41]
	v_lshl_add_u64 v[42:43], s[48:49], 0, v[42:43]
	v_lshl_add_u64 v[40:41], s[20:21], 0, v[40:41]
	v_lshl_add_u64 v[42:43], v[42:43], 0, v[142:143]
	v_lshl_add_u64 v[40:41], v[138:139], 1, v[40:41]
	s_waitcnt vmcnt(1)
	v_pk_fma_f32 v[30:31], v[30:31], 0.5, v[34:35] op_sel_hi:[1,0,1]
	v_pk_fma_f32 v[28:29], v[28:29], 0.5, v[32:33] op_sel_hi:[1,0,1]
	s_waitcnt vmcnt(0)
	v_pk_fma_f32 v[26:27], v[26:27], 0.5, v[38:39] op_sel_hi:[1,0,1]
	v_pk_fma_f32 v[24:25], v[24:25], 0.5, v[36:37] op_sel_hi:[1,0,1]
	v_cvt_pk_bf16_f32 v32, v28, v29
	v_cvt_pk_bf16_f32 v33, v30, v31
	v_cvt_pk_bf16_f32 v34, v24, v25
	v_cvt_pk_bf16_f32 v35, v26, v27
	global_store_dwordx4 v[42:43], v[28:31], off
	global_store_dwordx4 v[42:43], v[24:27], off offset:16
	global_store_dwordx4 v[40:41], v[32:35], off
	global_load_dwordx4 v[32:35], v[44:45], off offset:512 nt
	s_nop 0
	global_load_dwordx4 v[36:39], v[44:45], off offset:528 nt
	v_mul_f32_e32 v29, v29, v29
	v_mul_f32_e32 v31, v31, v31
	v_mul_f32_e32 v25, v25, v25
	v_fmac_f32_e32 v29, v28, v28
	v_fmac_f32_e32 v31, v30, v30
	v_mul_f32_e32 v27, v27, v27
	v_fmac_f32_e32 v25, v24, v24
	v_add_f32_e32 v24, v29, v31
	v_fmac_f32_e32 v27, v26, v26
	v_add_f32_e32 v24, v25, v24
	v_add_f32_e32 v28, v27, v24
	s_waitcnt vmcnt(1)
	v_pk_fma_f32 v[22:23], v[22:23], 0.5, v[34:35] op_sel_hi:[1,0,1]
	v_pk_fma_f32 v[20:21], v[20:21], 0.5, v[32:33] op_sel_hi:[1,0,1]
	s_waitcnt vmcnt(0)
	v_pk_fma_f32 v[24:25], v[16:17], 0.5, v[36:37] op_sel_hi:[1,0,1]
	v_mul_f32_e32 v16, v21, v21
	v_mul_f32_e32 v17, v23, v23
	v_pk_fma_f32 v[26:27], v[18:19], 0.5, v[38:39] op_sel_hi:[1,0,1]
	v_mul_f32_e32 v18, v25, v25
	v_fmac_f32_e32 v16, v20, v20
	v_fmac_f32_e32 v17, v22, v22
	v_mul_f32_e32 v19, v27, v27
	v_fmac_f32_e32 v18, v24, v24
	v_add_f32_e32 v16, v16, v17
	v_add_f32_e32 v16, v18, v16
	v_fmac_f32_e32 v19, v26, v26
	v_add_f32_e32 v16, v19, v16
	v_add_f32_e32 v16, v28, v16
	ds_bpermute_b32 v17, v121, v16
	global_store_dwordx4 v[42:43], v[20:23], off offset:512
	global_store_dwordx4 v[42:43], v[24:27], off offset:528
	v_cvt_pk_bf16_f32 v18, v20, v21
	v_cvt_pk_bf16_f32 v19, v22, v23
	v_cvt_pk_bf16_f32 v20, v24, v25
	s_waitcnt lgkmcnt(0)
	v_add_f32_e32 v16, v16, v17
	ds_bpermute_b32 v17, v120, v16
	v_cvt_pk_bf16_f32 v21, v26, v27
	global_store_dwordx4 v[40:41], v[18:21], off offset:256
	s_and_saveexec_b64 s[16:17], s[42:43]
	s_cbranch_execz .LBB0_187
	s_waitcnt lgkmcnt(0)
	v_add_f32_e32 v16, v16, v17
	v_mul_f32_e32 v16, 0x4b800000, v16
	v_trunc_f32_e32 v16, v16
	v_mul_f32_e32 v17, 0x2f800000, v16
	v_floor_f32_e32 v17, v17
	v_fmac_f32_e32 v16, 0xcf800000, v17
	v_cvt_u32_f32_e32 v16, v16
	v_cvt_u32_f32_e32 v17, v17
	global_atomic_add_x2 v[112:113], v[16:17], off offset:1280
.LBB0_187:
	s_or_b64 exec, exec, s[16:17]
	v_add_u32_e32 v16, 0xb0, v140
	s_waitcnt lgkmcnt(0)
	v_ashrrev_i32_e32 v17, 31, v16
	v_lshlrev_b64 v[18:19], 12, v[16:17]
	v_lshl_add_u64 v[20:21], s[48:49], 0, v[18:19]
	v_lshl_add_u64 v[18:19], s[2:3], 0, v[18:19]
	v_lshlrev_b64 v[16:17], 11, v[16:17]
	v_lshl_add_u64 v[26:27], v[18:19], 0, v[142:143]
	v_lshl_add_u64 v[16:17], s[20:21], 0, v[16:17]
	v_lshl_add_u64 v[24:25], v[20:21], 0, v[142:143]
	v_lshl_add_u64 v[28:29], v[138:139], 1, v[16:17]
	global_load_dwordx4 v[16:19], v[26:27], off offset:16 nt
	global_load_dwordx4 v[20:23], v[26:27], off nt
	s_waitcnt vmcnt(1)
	v_pk_fma_f32 v[10:11], v[10:11], 0.5, v[18:19] op_sel_hi:[1,0,1]
	s_waitcnt vmcnt(0)
	v_pk_fma_f32 v[14:15], v[14:15], 0.5, v[22:23] op_sel_hi:[1,0,1]
	v_pk_fma_f32 v[12:13], v[12:13], 0.5, v[20:21] op_sel_hi:[1,0,1]
	v_pk_fma_f32 v[8:9], v[8:9], 0.5, v[16:17] op_sel_hi:[1,0,1]
	global_store_dwordx4 v[24:25], v[12:15], off
	global_store_dwordx4 v[24:25], v[8:11], off offset:16
	v_cvt_pk_bf16_f32 v16, v12, v13
	v_mul_f32_e32 v13, v13, v13
	v_fmac_f32_e32 v13, v12, v12
	v_mul_f32_e32 v12, v15, v15
	v_cvt_pk_bf16_f32 v18, v8, v9
	v_fmac_f32_e32 v12, v14, v14
	v_mul_f32_e32 v9, v9, v9
	v_add_f32_e32 v12, v13, v12
	v_fmac_f32_e32 v9, v8, v8
	v_cvt_pk_bf16_f32 v17, v14, v15
	v_cvt_pk_bf16_f32 v19, v10, v11
	v_add_f32_e32 v8, v9, v12
	v_mul_f32_e32 v9, v11, v11
	global_store_dwordx4 v[28:29], v[16:19], off
	v_fmac_f32_e32 v9, v10, v10
	s_nop 0
	v_add_f32_e32 v16, v9, v8
	global_load_dwordx4 v[8:11], v[26:27], off offset:528 nt
	global_load_dwordx4 v[12:15], v[26:27], off offset:512 nt
	s_waitcnt vmcnt(1)
	v_pk_fma_f32 v[2:3], v[2:3], 0.5, v[10:11] op_sel_hi:[1,0,1]
	s_waitcnt vmcnt(0)
	v_pk_fma_f32 v[6:7], v[6:7], 0.5, v[14:15] op_sel_hi:[1,0,1]
	v_pk_fma_f32 v[4:5], v[4:5], 0.5, v[12:13] op_sel_hi:[1,0,1]
	v_pk_fma_f32 v[0:1], v[0:1], 0.5, v[8:9] op_sel_hi:[1,0,1]
	global_store_dwordx4 v[24:25], v[4:7], off offset:512
	global_store_dwordx4 v[24:25], v[0:3], off offset:528
	v_cvt_pk_bf16_f32 v8, v4, v5
	v_mul_f32_e32 v5, v5, v5
	v_fmac_f32_e32 v5, v4, v4
	v_mul_f32_e32 v4, v7, v7
	v_cvt_pk_bf16_f32 v10, v0, v1
	v_fmac_f32_e32 v4, v6, v6
	v_mul_f32_e32 v1, v1, v1
	v_add_f32_e32 v4, v5, v4
	v_fmac_f32_e32 v1, v0, v0
	v_add_f32_e32 v0, v1, v4
	v_mul_f32_e32 v1, v3, v3
	v_fmac_f32_e32 v1, v2, v2
	v_add_f32_e32 v0, v1, v0
	v_add_f32_e32 v0, v16, v0
	ds_bpermute_b32 v1, v121, v0
	v_cvt_pk_bf16_f32 v9, v6, v7
	v_cvt_pk_bf16_f32 v11, v2, v3
	global_store_dwordx4 v[28:29], v[8:11], off offset:256
	s_waitcnt lgkmcnt(0)
	v_add_f32_e32 v0, v0, v1
	ds_bpermute_b32 v1, v120, v0
	s_and_saveexec_b64 s[16:17], s[42:43]
	s_cbranch_execz .LBB0_189
	s_waitcnt lgkmcnt(0)
	v_add_f32_e32 v0, v0, v1
	v_mul_f32_e32 v0, 0x4b800000, v0
	v_trunc_f32_e32 v0, v0
	v_mul_f32_e32 v1, 0x2f800000, v0
	v_floor_f32_e32 v1, v1
	v_fmac_f32_e32 v0, 0xcf800000, v1
	v_cvt_u32_f32_e32 v0, v0
	v_cvt_u32_f32_e32 v1, v1
	global_atomic_add_x2 v[112:113], v[0:1], off offset:1408

; __device__ __forceinline__ unsigned cvtpk(float lo, float hi) { f32x2_t v = {lo, hi}; bf16x2_t b = __builtin_convertvector(v, bf16x2_t); return __builtin_bit_cast(unsigned, b); }
;     __device__ __forceinline__ void operator()(const Acc& acc, const Unit& u, int wr, int wc, int fr, int fq) const {
;     ...
;             for (int m = 0; m < 4; ++m) { const int row = row0 + ai * HALF + m * 16; float* rp = X + (size_t)row * DM + col0; const float* ip = Xin + (size_t)row * DM + col0; bf16_t* bp = XB + (size_t)row * DM + col0; float part = 0.f;
; #pragma unroll
;                 for (int bj = 0; bj < 2; ++bj) { f32x4* p = (f32x4*)(rp + bj * HALF); const f32x4* q = (const f32x4*)(ip + bj * HALF); f32x4 a = q[0], b = q[1]; a += acc[ai][bj][m][0] * scale; b += acc[ai][bj][m][1] * scale; p[0] = a; p[1] = b;
;                     *(u32x4*)(bp + bj * HALF) = (u32x4){cvtpk(a[0], a[1]), cvtpk(a[2], a[3]), cvtpk(b[0], b[1]), cvtpk(b[2], b[3])};
;                     part += (a[0] * a[0] + a[1] * a[1]) + (a[2] * a[2] + a[3] * a[3]) + (b[0] * b[0] + b[1] * b[1]) + (b[2] * b[2] + b[3] * b[3]); }
;                 part += __shfl_xor(part, 16); part += __shfl_xor(part, 32);
;                 if (fq == 0) __hip_atomic_fetch_add(SS + row, (u64)(part * SSF), __ATOMIC_RELAXED, __HIP_MEMORY_SCOPE_AGENT); }
.LBB0_1060:
	v_lshl_add_u32 v140, s46, 8, v142
	v_ashrrev_i32_e32 v141, 31, v140
	v_lshl_or_b32 v138, s52, 8, v144
	v_lshlrev_b64 v[146:147], 12, v[140:141]
	v_ashrrev_i32_e32 v139, 31, v138
	v_lshl_add_u64 v[146:147], s[48:49], 0, v[146:147]
	v_lshl_add_u64 v[158:159], v[138:139], 2, v[146:147]
	global_load_dwordx4 v[146:149], v[158:159], off nt
	global_load_dwordx4 v[150:153], v[158:159], off offset:16 nt
	v_lshlrev_b64 v[154:155], 11, v[140:141]
	v_lshl_add_u64 v[154:155], s[14:15], 0, v[154:155]
	v_lshl_add_u64 v[162:163], v[138:139], 1, v[154:155]
	s_waitcnt vmcnt(0)
	v_pk_add_f32 v[126:127], v[126:127], v[148:149]
	v_pk_add_f32 v[124:125], v[124:125], v[146:147]
	v_pk_add_f32 v[148:149], v[122:123], v[152:153]
	v_pk_add_f32 v[146:147], v[120:121], v[150:151]
	v_cvt_pk_bf16_f32 v120, v124, v125
	v_cvt_pk_bf16_f32 v121, v126, v127
	v_cvt_pk_bf16_f32 v122, v146, v147
	v_cvt_pk_bf16_f32 v123, v148, v149
	global_store_dwordx4 v[158:159], v[124:127], off
	global_store_dwordx4 v[158:159], v[146:149], off offset:16
	global_store_dwordx4 v[162:163], v[120:123], off
	global_load_dwordx4 v[150:153], v[158:159], off offset:512 nt
	global_load_dwordx4 v[154:157], v[158:159], off offset:528 nt
	v_and_b32_e32 v121, 64, v229
	v_xor_b32_e32 v120, 16, v229
	v_add_u32_e32 v121, 64, v121
	v_xor_b32_e32 v122, 32, v229
	v_cmp_lt_i32_e32 vcc, v120, v121
	v_mul_f32_e32 v123, v127, v127
	v_fmac_f32_e32 v123, v126, v126
	v_cndmask_b32_e32 v120, v229, v120, vcc
	v_cmp_lt_i32_e32 vcc, v122, v121
	v_lshlrev_b32_e32 v121, 2, v120
	v_mul_f32_e32 v127, v149, v149
	v_cndmask_b32_e32 v122, v229, v122, vcc
	v_lshlrev_b32_e32 v120, 2, v122
	v_mul_f32_e32 v122, v125, v125
	v_mul_f32_e32 v125, v147, v147
	v_fmac_f32_e32 v122, v124, v124
	v_fmac_f32_e32 v125, v146, v146
	v_add_f32_e32 v122, v122, v123
	v_fmac_f32_e32 v127, v148, v148
	v_add_f32_e32 v122, v125, v122
	v_add_f32_e32 v126, v127, v122
	s_waitcnt vmcnt(1)
	v_pk_add_f32 v[118:119], v[118:119], v[152:153]
	v_pk_add_f32 v[116:117], v[116:117], v[150:151]
	s_waitcnt vmcnt(0)
	v_pk_add_f32 v[122:123], v[112:113], v[154:155]
	v_mul_f32_e32 v112, v117, v117
	v_mul_f32_e32 v113, v119, v119
	v_pk_add_f32 v[124:125], v[114:115], v[156:157]
	v_mul_f32_e32 v114, v123, v123
	v_fmac_f32_e32 v112, v116, v116
	v_fmac_f32_e32 v113, v118, v118
	v_mul_f32_e32 v115, v125, v125
	v_fmac_f32_e32 v114, v122, v122
	v_add_f32_e32 v112, v112, v113
	v_add_f32_e32 v112, v114, v112
	v_fmac_f32_e32 v115, v124, v124
	v_add_f32_e32 v112, v115, v112
	v_add_f32_e32 v112, v126, v112
	ds_bpermute_b32 v113, v121, v112
	global_store_dwordx4 v[158:159], v[116:119], off offset:512
	global_store_dwordx4 v[158:159], v[122:125], off offset:528
	s_waitcnt lgkmcnt(0)
	v_add_f32_e32 v114, v112, v113
	ds_bpermute_b32 v115, v120, v114
	v_cvt_pk_bf16_f32 v116, v116, v117
	v_cvt_pk_bf16_f32 v117, v118, v119
	v_cvt_pk_bf16_f32 v118, v122, v123
	v_cvt_pk_bf16_f32 v119, v124, v125
	v_lshl_add_u64 v[112:113], v[140:141], 3, s[18:19]
	global_store_dwordx4 v[162:163], v[116:119], off offset:256
	s_and_saveexec_b64 s[16:17], s[42:43]
	s_cbranch_execz .LBB0_1062
	s_waitcnt lgkmcnt(0)
	v_add_f32_e32 v114, v114, v115
	v_mul_f32_e32 v114, 0x4b800000, v114
	v_trunc_f32_e32 v114, v114
	v_mul_f32_e32 v115, 0x2f800000, v114
	v_floor_f32_e32 v115, v115
	v_fmac_f32_e32 v114, 0xcf800000, v115
	v_cvt_u32_f32_e32 v114, v114
	v_cvt_u32_f32_e32 v115, v115
	global_atomic_add_x2 v[112:113], v[114:115], off
.LBB0_1062:
	s_or_b64 exec, exec, s[16:17]
	v_or_b32_e32 v118, 16, v140
	v_ashrrev_i32_e32 v119, 31, v118
	s_waitcnt lgkmcnt(0)
	v_lshlrev_b64 v[114:115], 12, v[118:119]
	v_lshl_add_u64 v[114:115], s[48:49], 0, v[114:115]
	v_lshl_add_u64 v[126:127], v[138:139], 2, v[114:115]
	global_load_dwordx4 v[114:117], v[126:127], off nt
	global_load_dwordx4 v[122:125], v[126:127], off offset:16 nt
	v_lshlrev_b64 v[118:119], 11, v[118:119]
	v_lshl_add_u64 v[118:119], s[14:15], 0, v[118:119]
	v_lshl_add_u64 v[118:119], v[138:139], 1, v[118:119]
	s_waitcnt vmcnt(1)
	v_pk_add_f32 v[110:111], v[110:111], v[116:117]
	v_pk_add_f32 v[108:109], v[108:109], v[114:115]
	s_waitcnt vmcnt(0)
	v_pk_add_f32 v[106:107], v[106:107], v[124:125]
	v_pk_add_f32 v[104:105], v[104:105], v[122:123]
	v_cvt_pk_bf16_f32 v114, v108, v109
	v_cvt_pk_bf16_f32 v115, v110, v111
	v_cvt_pk_bf16_f32 v116, v104, v105
	v_cvt_pk_bf16_f32 v117, v106, v107
	global_store_dwordx4 v[126:127], v[108:111], off
	global_store_dwordx4 v[126:127], v[104:107], off offset:16
	global_store_dwordx4 v[118:119], v[114:117], off
	global_load_dwordx4 v[114:117], v[126:127], off offset:512 nt
	s_nop 0
	global_load_dwordx4 v[122:125], v[126:127], off offset:528 nt
	v_mul_f32_e32 v109, v109, v109
	v_mul_f32_e32 v111, v111, v111
	v_mul_f32_e32 v105, v105, v105
	v_fmac_f32_e32 v109, v108, v108
	v_fmac_f32_e32 v111, v110, v110
	v_mul_f32_e32 v107, v107, v107
	v_fmac_f32_e32 v105, v104, v104
	v_add_f32_e32 v104, v109, v111
	v_fmac_f32_e32 v107, v106, v106
	v_add_f32_e32 v104, v105, v104
	v_add_f32_e32 v108, v107, v104
	s_waitcnt vmcnt(1)
	v_pk_add_f32 v[102:103], v[102:103], v[116:117]
	v_pk_add_f32 v[100:101], v[100:101], v[114:115]
	s_waitcnt vmcnt(0)
	v_pk_add_f32 v[104:105], v[96:97], v[122:123]
	v_mul_f32_e32 v96, v101, v101
	v_mul_f32_e32 v97, v103, v103
	v_pk_add_f32 v[106:107], v[98:99], v[124:125]
	v_mul_f32_e32 v98, v105, v105
	v_fmac_f32_e32 v96, v100, v100
	v_fmac_f32_e32 v97, v102, v102
	v_mul_f32_e32 v99, v107, v107
	v_fmac_f32_e32 v98, v104, v104
	v_add_f32_e32 v96, v96, v97
	v_add_f32_e32 v96, v98, v96
	v_fmac_f32_e32 v99, v106, v106
	v_add_f32_e32 v96, v99, v96
	v_add_f32_e32 v96, v108, v96
	ds_bpermute_b32 v97, v121, v96
	global_store_dwordx4 v[126:127], v[100:103], off offset:512
	global_store_dwordx4 v[126:127], v[104:107], off offset:528
	v_cvt_pk_bf16_f32 v98, v100, v101
	v_cvt_pk_bf16_f32 v99, v102, v103
	v_cvt_pk_bf16_f32 v100, v104, v105
	s_waitcnt lgkmcnt(0)
	v_add_f32_e32 v96, v96, v97
	ds_bpermute_b32 v97, v120, v96
	v_cvt_pk_bf16_f32 v101, v106, v107
	global_store_dwordx4 v[118:119], v[98:101], off offset:256
	s_and_saveexec_b64 s[16:17], s[42:43]
	s_cbranch_execz .LBB0_1064
	s_waitcnt lgkmcnt(0)
	v_add_f32_e32 v96, v96, v97
	v_mul_f32_e32 v96, 0x4b800000, v96
	v_trunc_f32_e32 v96, v96
	v_mul_f32_e32 v97, 0x2f800000, v96
	v_floor_f32_e32 v97, v97
	v_fmac_f32_e32 v96, 0xcf800000, v97
	v_cvt_u32_f32_e32 v96, v96
	v_cvt_u32_f32_e32 v97, v97
	global_atomic_add_x2 v[112:113], v[96:97], off offset:128
; __device__ __forceinline__ unsigned cvtpk(float lo, float hi) { f32x2_t v = {lo, hi}; bf16x2_t b = __builtin_convertvector(v, bf16x2_t); return __builtin_bit_cast(unsigned, b); }
;     __device__ __forceinline__ void operator()(const Acc& acc, const Unit& u, int wr, int wc, int fr, int fq) const {
;     ...
;             for (int m = 0; m < 4; ++m) { const int row = row0 + ai * HALF + m * 16; float* rp = X + (size_t)row * DM + col0; const float* ip = Xin + (size_t)row * DM + col0; bf16_t* bp = XB + (size_t)row * DM + col0; float part = 0.f;
; #pragma unroll
;                 for (int bj = 0; bj < 2; ++bj) { f32x4* p = (f32x4*)(rp + bj * HALF); const f32x4* q = (const f32x4*)(ip + bj * HALF); f32x4 a = q[0], b = q[1]; a += acc[ai][bj][m][0] * scale; b += acc[ai][bj][m][1] * scale; p[0] = a; p[1] = b;
;                     *(u32x4*)(bp + bj * HALF) = (u32x4){cvtpk(a[0], a[1]), cvtpk(a[2], a[3]), cvtpk(b[0], b[1]), cvtpk(b[2], b[3])};
;                     part += (a[0] * a[0] + a[1] * a[1]) + (a[2] * a[2] + a[3] * a[3]) + (b[0] * b[0] + b[1] * b[1]) + (b[2] * b[2] + b[3] * b[3]); }
;                 part += __shfl_xor(part, 16); part += __shfl_xor(part, 32);
;                 if (fq == 0) __hip_atomic_fetch_add(SS + row, (u64)(part * SSF), __ATOMIC_RELAXED, __HIP_MEMORY_SCOPE_AGENT); }
.LBB0_1064:
	s_or_b64 exec, exec, s[16:17]
	v_or_b32_e32 v104, 32, v140
	v_ashrrev_i32_e32 v105, 31, v104
	s_waitcnt lgkmcnt(0)
	v_lshlrev_b64 v[96:97], 12, v[104:105]
	v_lshl_add_u64 v[96:97], s[48:49], 0, v[96:97]
	v_lshl_add_u64 v[106:107], v[138:139], 2, v[96:97]
	global_load_dwordx4 v[96:99], v[106:107], off nt
	global_load_dwordx4 v[100:103], v[106:107], off offset:16 nt
	v_lshlrev_b64 v[104:105], 11, v[104:105]
	v_lshl_add_u64 v[104:105], s[14:15], 0, v[104:105]
	v_lshl_add_u64 v[104:105], v[138:139], 1, v[104:105]
	s_waitcnt vmcnt(1)
	v_pk_add_f32 v[94:95], v[94:95], v[98:99]
	v_pk_add_f32 v[92:93], v[92:93], v[96:97]
	s_waitcnt vmcnt(0)
	v_pk_add_f32 v[90:91], v[90:91], v[102:103]
	v_pk_add_f32 v[88:89], v[88:89], v[100:101]
	v_cvt_pk_bf16_f32 v96, v92, v93
	v_cvt_pk_bf16_f32 v97, v94, v95
	v_cvt_pk_bf16_f32 v98, v88, v89
	v_cvt_pk_bf16_f32 v99, v90, v91
	global_store_dwordx4 v[106:107], v[92:95], off
	global_store_dwordx4 v[106:107], v[88:91], off offset:16
	global_store_dwordx4 v[104:105], v[96:99], off
	global_load_dwordx4 v[96:99], v[106:107], off offset:512 nt
	s_nop 0
	global_load_dwordx4 v[100:103], v[106:107], off offset:528 nt
	v_mul_f32_e32 v93, v93, v93
	v_mul_f32_e32 v95, v95, v95
	v_mul_f32_e32 v89, v89, v89
	v_fmac_f32_e32 v93, v92, v92
	v_fmac_f32_e32 v95, v94, v94
	v_mul_f32_e32 v91, v91, v91
	v_fmac_f32_e32 v89, v88, v88
	v_add_f32_e32 v88, v93, v95
	v_fmac_f32_e32 v91, v90, v90
	v_add_f32_e32 v88, v89, v88
	v_add_f32_e32 v92, v91, v88
	s_waitcnt vmcnt(1)
	v_pk_add_f32 v[86:87], v[86:87], v[98:99]
	v_pk_add_f32 v[84:85], v[84:85], v[96:97]
	s_waitcnt vmcnt(0)
	v_pk_add_f32 v[88:89], v[80:81], v[100:101]
	v_mul_f32_e32 v80, v85, v85
	v_mul_f32_e32 v81, v87, v87
	v_pk_add_f32 v[90:91], v[82:83], v[102:103]
	v_mul_f32_e32 v82, v89, v89
	v_fmac_f32_e32 v80, v84, v84
	v_fmac_f32_e32 v81, v86, v86
	v_mul_f32_e32 v83, v91, v91
	v_fmac_f32_e32 v82, v88, v88
	v_add_f32_e32 v80, v80, v81
	v_add_f32_e32 v80, v82, v80
	v_fmac_f32_e32 v83, v90, v90
	v_add_f32_e32 v80, v83, v80
	v_add_f32_e32 v80, v92, v80
	ds_bpermute_b32 v81, v121, v80
	global_store_dwordx4 v[106:107], v[84:87], off offset:512
	global_store_dwordx4 v[106:107], v[88:91], off offset:528
	v_cvt_pk_bf16_f32 v82, v84, v85
	v_cvt_pk_bf16_f32 v83, v86, v87
	v_cvt_pk_bf16_f32 v84, v88, v89
	s_waitcnt lgkmcnt(0)
	v_add_f32_e32 v80, v80, v81
	ds_bpermute_b32 v81, v120, v80
	v_cvt_pk_bf16_f32 v85, v90, v91
	global_store_dwordx4 v[104:105], v[82:85], off offset:256
	s_and_saveexec_b64 s[16:17], s[42:43]
	s_cbranch_execz .LBB0_1066
	s_waitcnt lgkmcnt(0)
	v_add_f32_e32 v80, v80, v81
	v_mul_f32_e32 v80, 0x4b800000, v80
	v_trunc_f32_e32 v80, v80
	v_mul_f32_e32 v81, 0x2f800000, v80
	v_floor_f32_e32 v81, v81
	v_fmac_f32_e32 v80, 0xcf800000, v81
	v_cvt_u32_f32_e32 v80, v80
	v_cvt_u32_f32_e32 v81, v81
	global_atomic_add_x2 v[112:113], v[80:81], off offset:256
.LBB0_1066:
	s_or_b64 exec, exec, s[16:17]
	v_or_b32_e32 v88, 48, v140
	v_ashrrev_i32_e32 v89, 31, v88
	s_waitcnt lgkmcnt(0)
	v_lshlrev_b64 v[80:81], 12, v[88:89]
	v_lshl_add_u64 v[80:81], s[48:49], 0, v[80:81]
	v_lshl_add_u64 v[90:91], v[138:139], 2, v[80:81]
	global_load_dwordx4 v[80:83], v[90:91], off nt
	global_load_dwordx4 v[84:87], v[90:91], off offset:16 nt
	v_lshlrev_b64 v[88:89], 11, v[88:89]
	v_lshl_add_u64 v[88:89], s[14:15], 0, v[88:89]
	v_lshl_add_u64 v[88:89], v[138:139], 1, v[88:89]
	s_waitcnt vmcnt(1)
	v_pk_add_f32 v[78:79], v[78:79], v[82:83]
	v_pk_add_f32 v[76:77], v[76:77], v[80:81]
	s_waitcnt vmcnt(0)
	v_pk_add_f32 v[74:75], v[74:75], v[86:87]
	v_pk_add_f32 v[72:73], v[72:73], v[84:85]
	v_cvt_pk_bf16_f32 v80, v76, v77
	v_cvt_pk_bf16_f32 v81, v78, v79
	v_cvt_pk_bf16_f32 v82, v72, v73
	v_cvt_pk_bf16_f32 v83, v74, v75
	global_store_dwordx4 v[90:91], v[76:79], off
	global_store_dwordx4 v[90:91], v[72:75], off offset:16
	global_store_dwordx4 v[88:89], v[80:83], off
	global_load_dwordx4 v[80:83], v[90:91], off offset:512 nt
	s_nop 0
	global_load_dwordx4 v[84:87], v[90:91], off offset:528 nt
	v_mul_f32_e32 v77, v77, v77
	v_mul_f32_e32 v79, v79, v79
	v_mul_f32_e32 v73, v73, v73
	v_fmac_f32_e32 v77, v76, v76
	v_fmac_f32_e32 v79, v78, v78
	v_mul_f32_e32 v75, v75, v75
	v_fmac_f32_e32 v73, v72, v72
	v_add_f32_e32 v72, v77, v79
	v_fmac_f32_e32 v75, v74, v74
	v_add_f32_e32 v72, v73, v72
	v_add_f32_e32 v76, v75, v72
	s_waitcnt vmcnt(1)
	v_pk_add_f32 v[70:71], v[70:71], v[82:83]
	v_pk_add_f32 v[68:69], v[68:69], v[80:81]
	s_waitcnt vmcnt(0)
	v_pk_add_f32 v[72:73], v[64:65], v[84:85]
	v_mul_f32_e32 v64, v69, v69
	v_mul_f32_e32 v65, v71, v71
	v_pk_add_f32 v[74:75], v[66:67], v[86:87]
	v_mul_f32_e32 v66, v73, v73
	v_fmac_f32_e32 v64, v68, v68
	v_fmac_f32_e32 v65, v70, v70
	v_mul_f32_e32 v67, v75, v75
	v_fmac_f32_e32 v66, v72, v72
	v_add_f32_e32 v64, v64, v65
	v_add_f32_e32 v64, v66, v64
	v_fmac_f32_e32 v67, v74, v74
	v_add_f32_e32 v64, v67, v64
	v_add_f32_e32 v64, v76, v64
	ds_bpermute_b32 v65, v121, v64
	global_store_dwordx4 v[90:91], v[68:71], off offset:512
	global_store_dwordx4 v[90:91], v[72:75], off offset:528
	v_cvt_pk_bf16_f32 v66, v68, v69
	v_cvt_pk_bf16_f32 v67, v70, v71
	v_cvt_pk_bf16_f32 v68, v72, v73
	s_waitcnt lgkmcnt(0)
	v_add_f32_e32 v64, v64, v65
	ds_bpermute_b32 v65, v120, v64
	v_cvt_pk_bf16_f32 v69, v74, v75
	global_store_dwordx4 v[88:89], v[66:69], off offset:256
	s_and_saveexec_b64 s[16:17], s[42:43]
	s_cbranch_execz .LBB0_1068
	s_waitcnt lgkmcnt(0)
	v_add_f32_e32 v64, v64, v65
	v_mul_f32_e32 v64, 0x4b800000, v64
	v_trunc_f32_e32 v64, v64
	v_mul_f32_e32 v65, 0x2f800000, v64
	v_floor_f32_e32 v65, v65
	v_fmac_f32_e32 v64, 0xcf800000, v65
	v_cvt_u32_f32_e32 v64, v64
	v_cvt_u32_f32_e32 v65, v65
	global_atomic_add_x2 v[112:113], v[64:65], off offset:384
; __device__ __forceinline__ unsigned cvtpk(float lo, float hi) { f32x2_t v = {lo, hi}; bf16x2_t b = __builtin_convertvector(v, bf16x2_t); return __builtin_bit_cast(unsigned, b); }
;     __device__ __forceinline__ void operator()(const Acc& acc, const Unit& u, int wr, int wc, int fr, int fq) const {
;     ...
;             for (int m = 0; m < 4; ++m) { const int row = row0 + ai * HALF + m * 16; float* rp = X + (size_t)row * DM + col0; const float* ip = Xin + (size_t)row * DM + col0; bf16_t* bp = XB + (size_t)row * DM + col0; float part = 0.f;
; #pragma unroll
;                 for (int bj = 0; bj < 2; ++bj) { f32x4* p = (f32x4*)(rp + bj * HALF); const f32x4* q = (const f32x4*)(ip + bj * HALF); f32x4 a = q[0], b = q[1]; a += acc[ai][bj][m][0] * scale; b += acc[ai][bj][m][1] * scale; p[0] = a; p[1] = b;
;                     *(u32x4*)(bp + bj * HALF) = (u32x4){cvtpk(a[0], a[1]), cvtpk(a[2], a[3]), cvtpk(b[0], b[1]), cvtpk(b[2], b[3])};
;                     part += (a[0] * a[0] + a[1] * a[1]) + (a[2] * a[2] + a[3] * a[3]) + (b[0] * b[0] + b[1] * b[1]) + (b[2] * b[2] + b[3] * b[3]); }
;                 part += __shfl_xor(part, 16); part += __shfl_xor(part, 32);
;                 if (fq == 0) __hip_atomic_fetch_add(SS + row, (u64)(part * SSF), __ATOMIC_RELAXED, __HIP_MEMORY_SCOPE_AGENT); }
.LBB0_1068:
	s_or_b64 exec, exec, s[16:17]
	v_add_u32_e32 v72, 0x80, v140
	v_ashrrev_i32_e32 v73, 31, v72
	s_waitcnt lgkmcnt(0)
	v_lshlrev_b64 v[64:65], 12, v[72:73]
	v_lshl_add_u64 v[64:65], s[48:49], 0, v[64:65]
	v_lshl_add_u64 v[74:75], v[138:139], 2, v[64:65]
	global_load_dwordx4 v[64:67], v[74:75], off nt
	global_load_dwordx4 v[68:71], v[74:75], off offset:16 nt
	v_lshlrev_b64 v[72:73], 11, v[72:73]
	v_lshl_add_u64 v[72:73], s[14:15], 0, v[72:73]
	v_lshl_add_u64 v[72:73], v[138:139], 1, v[72:73]
	s_waitcnt vmcnt(1)
	v_pk_add_f32 v[62:63], v[62:63], v[66:67]
	v_pk_add_f32 v[60:61], v[60:61], v[64:65]
	s_waitcnt vmcnt(0)
	v_pk_add_f32 v[58:59], v[58:59], v[70:71]
	v_pk_add_f32 v[56:57], v[56:57], v[68:69]
	v_cvt_pk_bf16_f32 v64, v60, v61
	v_cvt_pk_bf16_f32 v65, v62, v63
	v_cvt_pk_bf16_f32 v66, v56, v57
	v_cvt_pk_bf16_f32 v67, v58, v59
	global_store_dwordx4 v[74:75], v[60:63], off
	global_store_dwordx4 v[74:75], v[56:59], off offset:16
	global_store_dwordx4 v[72:73], v[64:67], off
	global_load_dwordx4 v[64:67], v[74:75], off offset:512 nt
	s_nop 0
	global_load_dwordx4 v[68:71], v[74:75], off offset:528 nt
	v_mul_f32_e32 v61, v61, v61
	v_mul_f32_e32 v63, v63, v63
	v_mul_f32_e32 v57, v57, v57
	v_fmac_f32_e32 v61, v60, v60
	v_fmac_f32_e32 v63, v62, v62
	v_mul_f32_e32 v59, v59, v59
	v_fmac_f32_e32 v57, v56, v56
	v_add_f32_e32 v56, v61, v63
	v_fmac_f32_e32 v59, v58, v58
	v_add_f32_e32 v56, v57, v56
	v_add_f32_e32 v60, v59, v56
	s_waitcnt vmcnt(1)
	v_pk_add_f32 v[54:55], v[54:55], v[66:67]
	v_pk_add_f32 v[52:53], v[52:53], v[64:65]
	s_waitcnt vmcnt(0)
	v_pk_add_f32 v[56:57], v[48:49], v[68:69]
	v_mul_f32_e32 v48, v53, v53
	v_mul_f32_e32 v49, v55, v55
	v_pk_add_f32 v[58:59], v[50:51], v[70:71]
	v_mul_f32_e32 v50, v57, v57
	v_fmac_f32_e32 v48, v52, v52
	v_fmac_f32_e32 v49, v54, v54
	v_mul_f32_e32 v51, v59, v59
	v_fmac_f32_e32 v50, v56, v56
	v_add_f32_e32 v48, v48, v49
	v_add_f32_e32 v48, v50, v48
	v_fmac_f32_e32 v51, v58, v58
	v_add_f32_e32 v48, v51, v48
	v_add_f32_e32 v48, v60, v48
	ds_bpermute_b32 v49, v121, v48
	global_store_dwordx4 v[74:75], v[52:55], off offset:512
	global_store_dwordx4 v[74:75], v[56:59], off offset:528
	v_cvt_pk_bf16_f32 v50, v52, v53
	v_cvt_pk_bf16_f32 v51, v54, v55
	v_cvt_pk_bf16_f32 v52, v56, v57
	s_waitcnt lgkmcnt(0)
	v_add_f32_e32 v48, v48, v49
	ds_bpermute_b32 v49, v120, v48
	v_cvt_pk_bf16_f32 v53, v58, v59
	global_store_dwordx4 v[72:73], v[50:53], off offset:256
	s_and_saveexec_b64 s[16:17], s[42:43]
	s_cbranch_execz .LBB0_1070
	s_waitcnt lgkmcnt(0)
	v_add_f32_e32 v48, v48, v49
	v_mul_f32_e32 v48, 0x4b800000, v48
	v_trunc_f32_e32 v48, v48
	v_mul_f32_e32 v49, 0x2f800000, v48
	v_floor_f32_e32 v49, v49
	v_fmac_f32_e32 v48, 0xcf800000, v49
	v_cvt_u32_f32_e32 v48, v48
	v_cvt_u32_f32_e32 v49, v49
	global_atomic_add_x2 v[112:113], v[48:49], off offset:1024
.LBB0_1070:
	s_or_b64 exec, exec, s[16:17]
	v_add_u32_e32 v56, 0x90, v140
	v_ashrrev_i32_e32 v57, 31, v56
	s_waitcnt lgkmcnt(0)
	v_lshlrev_b64 v[48:49], 12, v[56:57]
	v_lshl_add_u64 v[48:49], s[48:49], 0, v[48:49]
	v_lshl_add_u64 v[58:59], v[138:139], 2, v[48:49]
	global_load_dwordx4 v[48:51], v[58:59], off nt
	global_load_dwordx4 v[52:55], v[58:59], off offset:16 nt
	v_lshlrev_b64 v[56:57], 11, v[56:57]
	v_lshl_add_u64 v[56:57], s[14:15], 0, v[56:57]
	v_lshl_add_u64 v[56:57], v[138:139], 1, v[56:57]
	s_waitcnt vmcnt(1)
	v_pk_add_f32 v[46:47], v[46:47], v[50:51]
	v_pk_add_f32 v[44:45], v[44:45], v[48:49]
	s_waitcnt vmcnt(0)
	v_pk_add_f32 v[42:43], v[42:43], v[54:55]
	v_pk_add_f32 v[40:41], v[40:41], v[52:53]
	v_cvt_pk_bf16_f32 v48, v44, v45
	v_cvt_pk_bf16_f32 v49, v46, v47
	v_cvt_pk_bf16_f32 v50, v40, v41
	v_cvt_pk_bf16_f32 v51, v42, v43
	global_store_dwordx4 v[58:59], v[44:47], off
	global_store_dwordx4 v[58:59], v[40:43], off offset:16
	global_store_dwordx4 v[56:57], v[48:51], off
	global_load_dwordx4 v[48:51], v[58:59], off offset:512 nt
	s_nop 0
	global_load_dwordx4 v[52:55], v[58:59], off offset:528 nt
	v_mul_f32_e32 v45, v45, v45
	v_mul_f32_e32 v47, v47, v47
	v_mul_f32_e32 v41, v41, v41
	v_fmac_f32_e32 v45, v44, v44
	v_fmac_f32_e32 v47, v46, v46
	v_mul_f32_e32 v43, v43, v43
	v_fmac_f32_e32 v41, v40, v40
	v_add_f32_e32 v40, v45, v47
	v_fmac_f32_e32 v43, v42, v42
	v_add_f32_e32 v40, v41, v40
	v_add_f32_e32 v44, v43, v40
	s_waitcnt vmcnt(1)
	v_pk_add_f32 v[38:39], v[38:39], v[50:51]
	v_pk_add_f32 v[36:37], v[36:37], v[48:49]
	s_waitcnt vmcnt(0)
	v_pk_add_f32 v[40:41], v[32:33], v[52:53]
	v_mul_f32_e32 v32, v37, v37
	v_mul_f32_e32 v33, v39, v39
	v_pk_add_f32 v[42:43], v[34:35], v[54:55]
	v_mul_f32_e32 v34, v41, v41
	v_fmac_f32_e32 v32, v36, v36
	v_fmac_f32_e32 v33, v38, v38
	v_mul_f32_e32 v35, v43, v43
	v_fmac_f32_e32 v34, v40, v40
	v_add_f32_e32 v32, v32, v33
	v_add_f32_e32 v32, v34, v32
	v_fmac_f32_e32 v35, v42, v42
	v_add_f32_e32 v32, v35, v32
	v_add_f32_e32 v32, v44, v32
	ds_bpermute_b32 v33, v121, v32
	global_store_dwordx4 v[58:59], v[36:39], off offset:512
	global_store_dwordx4 v[58:59], v[40:43], off offset:528
	v_cvt_pk_bf16_f32 v34, v36, v37
	v_cvt_pk_bf16_f32 v35, v38, v39
	v_cvt_pk_bf16_f32 v36, v40, v41
	s_waitcnt lgkmcnt(0)
	v_add_f32_e32 v32, v32, v33
	ds_bpermute_b32 v33, v120, v32
	v_cvt_pk_bf16_f32 v37, v42, v43
	global_store_dwordx4 v[56:57], v[34:37], off offset:256
	s_and_saveexec_b64 s[16:17], s[42:43]
	s_cbranch_execz .LBB0_1072
	s_waitcnt lgkmcnt(0)
	v_add_f32_e32 v32, v32, v33
	v_mul_f32_e32 v32, 0x4b800000, v32
	v_trunc_f32_e32 v32, v32
	v_mul_f32_e32 v33, 0x2f800000, v32
	v_floor_f32_e32 v33, v33
	v_fmac_f32_e32 v32, 0xcf800000, v33
	v_cvt_u32_f32_e32 v32, v32
	v_cvt_u32_f32_e32 v33, v33
	global_atomic_add_x2 v[112:113], v[32:33], off offset:1152
; __device__ __forceinline__ unsigned cvtpk(float lo, float hi) { f32x2_t v = {lo, hi}; bf16x2_t b = __builtin_convertvector(v, bf16x2_t); return __builtin_bit_cast(unsigned, b); }
;     __device__ __forceinline__ void operator()(const Acc& acc, const Unit& u, int wr, int wc, int fr, int fq) const {
;     ...
;             for (int m = 0; m < 4; ++m) { const int row = row0 + ai * HALF + m * 16; float* rp = X + (size_t)row * DM + col0; const float* ip = Xin + (size_t)row * DM + col0; bf16_t* bp = XB + (size_t)row * DM + col0; float part = 0.f;
; #pragma unroll
;                 for (int bj = 0; bj < 2; ++bj) { f32x4* p = (f32x4*)(rp + bj * HALF); const f32x4* q = (const f32x4*)(ip + bj * HALF); f32x4 a = q[0], b = q[1]; a += acc[ai][bj][m][0] * scale; b += acc[ai][bj][m][1] * scale; p[0] = a; p[1] = b;
;                     *(u32x4*)(bp + bj * HALF) = (u32x4){cvtpk(a[0], a[1]), cvtpk(a[2], a[3]), cvtpk(b[0], b[1]), cvtpk(b[2], b[3])};
;                     part += (a[0] * a[0] + a[1] * a[1]) + (a[2] * a[2] + a[3] * a[3]) + (b[0] * b[0] + b[1] * b[1]) + (b[2] * b[2] + b[3] * b[3]); }
;                 part += __shfl_xor(part, 16); part += __shfl_xor(part, 32);
;                 if (fq == 0) __hip_atomic_fetch_add(SS + row, (u64)(part * SSF), __ATOMIC_RELAXED, __HIP_MEMORY_SCOPE_AGENT); }
.LBB0_1072:
	s_or_b64 exec, exec, s[16:17]
	v_add_u32_e32 v40, 0xa0, v140
	v_ashrrev_i32_e32 v41, 31, v40
	s_waitcnt lgkmcnt(0)
	v_lshlrev_b64 v[32:33], 12, v[40:41]
	v_lshl_add_u64 v[32:33], s[48:49], 0, v[32:33]
	v_lshl_add_u64 v[42:43], v[138:139], 2, v[32:33]
	global_load_dwordx4 v[32:35], v[42:43], off nt
	global_load_dwordx4 v[36:39], v[42:43], off offset:16 nt
	v_lshlrev_b64 v[40:41], 11, v[40:41]
	v_lshl_add_u64 v[40:41], s[14:15], 0, v[40:41]
	v_lshl_add_u64 v[40:41], v[138:139], 1, v[40:41]
	s_waitcnt vmcnt(1)
	v_pk_add_f32 v[30:31], v[30:31], v[34:35]
	v_pk_add_f32 v[28:29], v[28:29], v[32:33]
	s_waitcnt vmcnt(0)
	v_pk_add_f32 v[26:27], v[26:27], v[38:39]
	v_pk_add_f32 v[24:25], v[24:25], v[36:37]
	v_cvt_pk_bf16_f32 v32, v28, v29
	v_cvt_pk_bf16_f32 v33, v30, v31
	v_cvt_pk_bf16_f32 v34, v24, v25
	v_cvt_pk_bf16_f32 v35, v26, v27
	global_store_dwordx4 v[42:43], v[28:31], off
	global_store_dwordx4 v[42:43], v[24:27], off offset:16
	global_store_dwordx4 v[40:41], v[32:35], off
	global_load_dwordx4 v[32:35], v[42:43], off offset:512 nt
	s_nop 0
	global_load_dwordx4 v[36:39], v[42:43], off offset:528 nt
	v_mul_f32_e32 v29, v29, v29
	v_mul_f32_e32 v31, v31, v31
	v_mul_f32_e32 v25, v25, v25
	v_fmac_f32_e32 v29, v28, v28
	v_fmac_f32_e32 v31, v30, v30
	v_mul_f32_e32 v27, v27, v27
	v_fmac_f32_e32 v25, v24, v24
	v_add_f32_e32 v24, v29, v31
	v_fmac_f32_e32 v27, v26, v26
	v_add_f32_e32 v24, v25, v24
	v_add_f32_e32 v28, v27, v24
	s_waitcnt vmcnt(1)
	v_pk_add_f32 v[22:23], v[22:23], v[34:35]
	v_pk_add_f32 v[20:21], v[20:21], v[32:33]
	s_waitcnt vmcnt(0)
	v_pk_add_f32 v[24:25], v[16:17], v[36:37]
	v_mul_f32_e32 v16, v21, v21
	v_mul_f32_e32 v17, v23, v23
	v_pk_add_f32 v[26:27], v[18:19], v[38:39]
	v_mul_f32_e32 v18, v25, v25
	v_fmac_f32_e32 v16, v20, v20
	v_fmac_f32_e32 v17, v22, v22
	v_mul_f32_e32 v19, v27, v27
	v_fmac_f32_e32 v18, v24, v24
	v_add_f32_e32 v16, v16, v17
	v_add_f32_e32 v16, v18, v16
	v_fmac_f32_e32 v19, v26, v26
	v_add_f32_e32 v16, v19, v16
	v_add_f32_e32 v16, v28, v16
	ds_bpermute_b32 v17, v121, v16
	global_store_dwordx4 v[42:43], v[20:23], off offset:512
	global_store_dwordx4 v[42:43], v[24:27], off offset:528
	v_cvt_pk_bf16_f32 v18, v20, v21
	v_cvt_pk_bf16_f32 v19, v22, v23
	v_cvt_pk_bf16_f32 v20, v24, v25
	s_waitcnt lgkmcnt(0)
	v_add_f32_e32 v16, v16, v17
	ds_bpermute_b32 v17, v120, v16
	v_cvt_pk_bf16_f32 v21, v26, v27
	global_store_dwordx4 v[40:41], v[18:21], off offset:256
	s_and_saveexec_b64 s[16:17], s[42:43]
	s_cbranch_execz .LBB0_1074
	s_waitcnt lgkmcnt(0)
	v_add_f32_e32 v16, v16, v17
	v_mul_f32_e32 v16, 0x4b800000, v16
	v_trunc_f32_e32 v16, v16
	v_mul_f32_e32 v17, 0x2f800000, v16
	v_floor_f32_e32 v17, v17
	v_fmac_f32_e32 v16, 0xcf800000, v17
	v_cvt_u32_f32_e32 v16, v16
	v_cvt_u32_f32_e32 v17, v17
	global_atomic_add_x2 v[112:113], v[16:17], off offset:1280
.LBB0_1074:
	s_or_b64 exec, exec, s[16:17]
	v_add_u32_e32 v16, 0xb0, v140
	s_waitcnt lgkmcnt(0)
	v_ashrrev_i32_e32 v17, 31, v16
	v_lshlrev_b64 v[18:19], 12, v[16:17]
	v_lshl_add_u64 v[18:19], s[48:49], 0, v[18:19]
	v_lshlrev_b64 v[16:17], 11, v[16:17]
	v_lshl_add_u64 v[24:25], v[138:139], 2, v[18:19]
	v_lshl_add_u64 v[16:17], s[14:15], 0, v[16:17]
	v_lshl_add_u64 v[26:27], v[138:139], 1, v[16:17]
	global_load_dwordx4 v[16:19], v[24:25], off offset:16 nt
	global_load_dwordx4 v[20:23], v[24:25], off nt
	s_waitcnt vmcnt(1)
	v_pk_add_f32 v[10:11], v[10:11], v[18:19]
	s_waitcnt vmcnt(0)
	v_pk_add_f32 v[14:15], v[14:15], v[22:23]
	v_pk_add_f32 v[12:13], v[12:13], v[20:21]
	v_pk_add_f32 v[8:9], v[8:9], v[16:17]
	global_store_dwordx4 v[24:25], v[12:15], off
	global_store_dwordx4 v[24:25], v[8:11], off offset:16
	v_cvt_pk_bf16_f32 v16, v12, v13
	v_mul_f32_e32 v13, v13, v13
	v_fmac_f32_e32 v13, v12, v12
	v_mul_f32_e32 v12, v15, v15
	v_cvt_pk_bf16_f32 v18, v8, v9
	v_fmac_f32_e32 v12, v14, v14
	v_mul_f32_e32 v9, v9, v9
	v_add_f32_e32 v12, v13, v12
	v_fmac_f32_e32 v9, v8, v8
	v_cvt_pk_bf16_f32 v17, v14, v15
	v_cvt_pk_bf16_f32 v19, v10, v11
	v_add_f32_e32 v8, v9, v12
	v_mul_f32_e32 v9, v11, v11
	global_store_dwordx4 v[26:27], v[16:19], off
	v_fmac_f32_e32 v9, v10, v10
	s_nop 0
	v_add_f32_e32 v16, v9, v8
	global_load_dwordx4 v[8:11], v[24:25], off offset:528 nt
	global_load_dwordx4 v[12:15], v[24:25], off offset:512 nt
	s_waitcnt vmcnt(1)
	v_pk_add_f32 v[2:3], v[2:3], v[10:11]
	s_waitcnt vmcnt(0)
	v_pk_add_f32 v[6:7], v[6:7], v[14:15]
	v_pk_add_f32 v[4:5], v[4:5], v[12:13]
	v_pk_add_f32 v[0:1], v[0:1], v[8:9]
	global_store_dwordx4 v[24:25], v[4:7], off offset:512
	global_store_dwordx4 v[24:25], v[0:3], off offset:528
	v_cvt_pk_bf16_f32 v8, v4, v5
	v_mul_f32_e32 v5, v5, v5
	v_fmac_f32_e32 v5, v4, v4
	v_mul_f32_e32 v4, v7, v7
	v_cvt_pk_bf16_f32 v10, v0, v1
	v_fmac_f32_e32 v4, v6, v6
	v_mul_f32_e32 v1, v1, v1
	v_add_f32_e32 v4, v5, v4
	v_fmac_f32_e32 v1, v0, v0
	v_add_f32_e32 v0, v1, v4
	v_mul_f32_e32 v1, v3, v3
	v_fmac_f32_e32 v1, v2, v2
	v_add_f32_e32 v0, v1, v0
	v_add_f32_e32 v0, v16, v0
	ds_bpermute_b32 v1, v121, v0
	v_cvt_pk_bf16_f32 v9, v6, v7
	v_cvt_pk_bf16_f32 v11, v2, v3
	global_store_dwordx4 v[26:27], v[8:11], off offset:256
	s_waitcnt lgkmcnt(0)
	v_add_f32_e32 v0, v0, v1
	ds_bpermute_b32 v1, v120, v0
	s_and_saveexec_b64 s[16:17], s[42:43]
	s_cbranch_execz .LBB0_1076
	s_waitcnt lgkmcnt(0)
	v_add_f32_e32 v0, v0, v1
	v_mul_f32_e32 v0, 0x4b800000, v0
	v_trunc_f32_e32 v0, v0
	v_mul_f32_e32 v1, 0x2f800000, v0
	v_floor_f32_e32 v1, v1
	v_fmac_f32_e32 v0, 0xcf800000, v1
	v_cvt_u32_f32_e32 v0, v0
	v_cvt_u32_f32_e32 v1, v1
	global_atomic_add_x2 v[112:113], v[0:1], off offset:1408

; __device__ __forceinline__ unsigned cvtpk(float lo, float hi) { f32x2_t v = {lo, hi}; bf16x2_t b = __builtin_convertvector(v, bf16x2_t); return __builtin_bit_cast(unsigned, b); }
;     __device__ __forceinline__ void operator()(const Acc& acc, const Unit& u, int wr, int wc, int fr, int fq) const {
;     ...
;             for (int m = 0; m < 4; ++m) { const int row = row0 + ai * HALF + m * 16; float* rp = X + (size_t)row * DM + col0; const float* ip = Xin + (size_t)row * DM + col0; bf16_t* bp = XB + (size_t)row * DM + col0; float part = 0.f;
; #pragma unroll
;                 for (int bj = 0; bj < 2; ++bj) { f32x4* p = (f32x4*)(rp + bj * HALF); const f32x4* q = (const f32x4*)(ip + bj * HALF); f32x4 a = q[0], b = q[1]; a += acc[ai][bj][m][0] * scale; b += acc[ai][bj][m][1] * scale; p[0] = a; p[1] = b;
;                     *(u32x4*)(bp + bj * HALF) = (u32x4){cvtpk(a[0], a[1]), cvtpk(a[2], a[3]), cvtpk(b[0], b[1]), cvtpk(b[2], b[3])};
;                     part += (a[0] * a[0] + a[1] * a[1]) + (a[2] * a[2] + a[3] * a[3]) + (b[0] * b[0] + b[1] * b[1]) + (b[2] * b[2] + b[3] * b[3]); }
;                 part += __shfl_xor(part, 16); part += __shfl_xor(part, 32);
;                 if (fq == 0) __hip_atomic_fetch_add(SS + row, (u64)(part * SSF), __ATOMIC_RELAXED, __HIP_MEMORY_SCOPE_AGENT); }
.LBB0_1260:
	v_lshl_add_u32 v140, s64, 8, v142
	v_ashrrev_i32_e32 v141, 31, v140
	v_lshl_or_b32 v138, s65, 8, v144
	v_lshlrev_b64 v[146:147], 12, v[140:141]
	v_ashrrev_i32_e32 v139, 31, v138
	v_lshl_add_u64 v[146:147], s[48:49], 0, v[146:147]
	v_lshl_add_u64 v[158:159], v[138:139], 2, v[146:147]
	global_load_dwordx4 v[146:149], v[158:159], off nt
	global_load_dwordx4 v[150:153], v[158:159], off offset:16 nt
	v_lshlrev_b64 v[154:155], 11, v[140:141]
	v_lshl_add_u64 v[154:155], s[14:15], 0, v[154:155]
	v_lshl_add_u64 v[162:163], v[138:139], 1, v[154:155]
	s_waitcnt vmcnt(0)
	v_pk_fma_f32 v[126:127], v[126:127], 0.5, v[148:149] op_sel_hi:[1,0,1]
	v_pk_fma_f32 v[124:125], v[124:125], 0.5, v[146:147] op_sel_hi:[1,0,1]
	v_pk_fma_f32 v[148:149], v[122:123], 0.5, v[152:153] op_sel_hi:[1,0,1]
	v_pk_fma_f32 v[146:147], v[120:121], 0.5, v[150:151] op_sel_hi:[1,0,1]
	v_cvt_pk_bf16_f32 v120, v124, v125
	v_cvt_pk_bf16_f32 v121, v126, v127
	v_cvt_pk_bf16_f32 v122, v146, v147
	v_cvt_pk_bf16_f32 v123, v148, v149
	global_store_dwordx4 v[158:159], v[124:127], off
	global_store_dwordx4 v[158:159], v[146:149], off offset:16
	global_store_dwordx4 v[162:163], v[120:123], off
	global_load_dwordx4 v[150:153], v[158:159], off offset:512 nt
	global_load_dwordx4 v[154:157], v[158:159], off offset:528 nt
	v_and_b32_e32 v121, 64, v229
	v_xor_b32_e32 v120, 16, v229
	v_add_u32_e32 v121, 64, v121
	v_xor_b32_e32 v122, 32, v229
	v_cmp_lt_i32_e32 vcc, v120, v121
	v_mul_f32_e32 v123, v127, v127
	v_fmac_f32_e32 v123, v126, v126
	v_cndmask_b32_e32 v120, v229, v120, vcc
	v_cmp_lt_i32_e32 vcc, v122, v121
	v_mul_f32_e32 v127, v149, v149
	v_fmac_f32_e32 v127, v148, v148
	v_cndmask_b32_e32 v121, v229, v122, vcc
	v_mul_f32_e32 v122, v125, v125
	v_mul_f32_e32 v125, v147, v147
	v_fmac_f32_e32 v122, v124, v124
	v_fmac_f32_e32 v125, v146, v146
	v_add_f32_e32 v122, v122, v123
	v_add_f32_e32 v122, v125, v122
	v_add_f32_e32 v126, v127, v122
	v_lshlrev_b32_e32 v120, 2, v120
	s_waitcnt vmcnt(1)
	v_pk_fma_f32 v[118:119], v[118:119], 0.5, v[152:153] op_sel_hi:[1,0,1]
	v_pk_fma_f32 v[116:117], v[116:117], 0.5, v[150:151] op_sel_hi:[1,0,1]
	s_waitcnt vmcnt(0)
	v_pk_fma_f32 v[122:123], v[112:113], 0.5, v[154:155] op_sel_hi:[1,0,1]
	v_mul_f32_e32 v112, v117, v117
	v_mul_f32_e32 v113, v119, v119
	v_pk_fma_f32 v[124:125], v[114:115], 0.5, v[156:157] op_sel_hi:[1,0,1]
	v_mul_f32_e32 v114, v123, v123
	v_fmac_f32_e32 v112, v116, v116
	v_fmac_f32_e32 v113, v118, v118
	v_mul_f32_e32 v115, v125, v125
	v_fmac_f32_e32 v114, v122, v122
	v_add_f32_e32 v112, v112, v113
	v_add_f32_e32 v112, v114, v112
	v_fmac_f32_e32 v115, v124, v124
	v_add_f32_e32 v112, v115, v112
	v_add_f32_e32 v112, v126, v112
	ds_bpermute_b32 v113, v120, v112
	v_lshlrev_b32_e32 v114, 2, v121
	global_store_dwordx4 v[158:159], v[116:119], off offset:512
	global_store_dwordx4 v[158:159], v[122:125], off offset:528
	s_waitcnt lgkmcnt(0)
	v_add_f32_e32 v112, v112, v113
	ds_bpermute_b32 v113, v114, v112
	v_cvt_pk_bf16_f32 v116, v116, v117
	v_cvt_pk_bf16_f32 v117, v118, v119
	v_cvt_pk_bf16_f32 v118, v122, v123
	v_cvt_pk_bf16_f32 v119, v124, v125
	global_store_dwordx4 v[162:163], v[116:119], off offset:256
	s_and_saveexec_b64 s[16:17], s[40:41]
	s_cbranch_execz .LBB0_1262
	s_waitcnt lgkmcnt(0)
	v_add_f32_e32 v112, v112, v113
	v_mul_f32_e32 v112, 0x4b800000, v112
	v_trunc_f32_e32 v112, v112
	v_mul_f32_e32 v113, 0x2f800000, v112
	v_floor_f32_e32 v113, v113
	v_fmac_f32_e32 v112, 0xcf800000, v113
	v_cvt_u32_f32_e32 v112, v112
	v_cvt_u32_f32_e32 v113, v113
	v_lshl_add_u64 v[116:117], v[140:141], 3, s[18:19]
	global_atomic_add_x2 v[116:117], v[112:113], off
.LBB0_1262:
	s_or_b64 exec, exec, s[16:17]
	v_or_b32_e32 v112, 16, v140
	s_waitcnt lgkmcnt(0)
	v_ashrrev_i32_e32 v113, 31, v112
	v_lshlrev_b64 v[116:117], 12, v[112:113]
	v_lshl_add_u64 v[116:117], s[48:49], 0, v[116:117]
	v_lshl_add_u64 v[126:127], v[138:139], 2, v[116:117]
	global_load_dwordx4 v[116:119], v[126:127], off nt
	global_load_dwordx4 v[122:125], v[126:127], off offset:16 nt
	v_lshlrev_b64 v[146:147], 11, v[112:113]
	v_lshl_add_u64 v[146:147], s[14:15], 0, v[146:147]
	v_lshl_add_u64 v[146:147], v[138:139], 1, v[146:147]
	s_waitcnt vmcnt(1)
	v_pk_fma_f32 v[110:111], v[110:111], 0.5, v[118:119] op_sel_hi:[1,0,1]
	v_pk_fma_f32 v[108:109], v[108:109], 0.5, v[116:117] op_sel_hi:[1,0,1]
	s_waitcnt vmcnt(0)
	v_pk_fma_f32 v[106:107], v[106:107], 0.5, v[124:125] op_sel_hi:[1,0,1]
	v_pk_fma_f32 v[104:105], v[104:105], 0.5, v[122:123] op_sel_hi:[1,0,1]
	v_cvt_pk_bf16_f32 v116, v108, v109
	v_cvt_pk_bf16_f32 v117, v110, v111
	v_cvt_pk_bf16_f32 v118, v104, v105
	v_cvt_pk_bf16_f32 v119, v106, v107
	global_store_dwordx4 v[126:127], v[108:111], off
	global_store_dwordx4 v[126:127], v[104:107], off offset:16
	global_store_dwordx4 v[146:147], v[116:119], off
	global_load_dwordx4 v[116:119], v[126:127], off offset:512 nt
	s_nop 0
	global_load_dwordx4 v[122:125], v[126:127], off offset:528 nt
	v_mul_f32_e32 v109, v109, v109
	v_mul_f32_e32 v111, v111, v111
	v_mul_f32_e32 v105, v105, v105
	v_fmac_f32_e32 v109, v108, v108
	v_fmac_f32_e32 v111, v110, v110
	v_mul_f32_e32 v107, v107, v107
	v_fmac_f32_e32 v105, v104, v104
	v_add_f32_e32 v104, v109, v111
	v_fmac_f32_e32 v107, v106, v106
	v_add_f32_e32 v104, v105, v104
	v_add_f32_e32 v108, v107, v104
	s_waitcnt vmcnt(1)
	v_pk_fma_f32 v[102:103], v[102:103], 0.5, v[118:119] op_sel_hi:[1,0,1]
	v_pk_fma_f32 v[100:101], v[100:101], 0.5, v[116:117] op_sel_hi:[1,0,1]
	s_waitcnt vmcnt(0)
	v_pk_fma_f32 v[104:105], v[96:97], 0.5, v[122:123] op_sel_hi:[1,0,1]
	v_mul_f32_e32 v96, v101, v101
	v_mul_f32_e32 v97, v103, v103
	v_pk_fma_f32 v[106:107], v[98:99], 0.5, v[124:125] op_sel_hi:[1,0,1]
	v_mul_f32_e32 v98, v105, v105
	v_fmac_f32_e32 v96, v100, v100
	v_fmac_f32_e32 v97, v102, v102
	v_mul_f32_e32 v99, v107, v107
	v_fmac_f32_e32 v98, v104, v104
	v_add_f32_e32 v96, v96, v97
	v_add_f32_e32 v96, v98, v96
	v_fmac_f32_e32 v99, v106, v106
	v_add_f32_e32 v96, v99, v96
	v_add_f32_e32 v96, v108, v96
	ds_bpermute_b32 v97, v120, v96
	global_store_dwordx4 v[126:127], v[100:103], off offset:512
	global_store_dwordx4 v[126:127], v[104:107], off offset:528
	v_cvt_pk_bf16_f32 v98, v100, v101
	v_cvt_pk_bf16_f32 v99, v102, v103
	v_cvt_pk_bf16_f32 v100, v104, v105
	s_waitcnt lgkmcnt(0)
	v_add_f32_e32 v96, v96, v97
	ds_bpermute_b32 v97, v114, v96
	v_cvt_pk_bf16_f32 v101, v106, v107
	global_store_dwordx4 v[146:147], v[98:101], off offset:256
	s_and_saveexec_b64 s[16:17], s[40:41]
	s_cbranch_execz .LBB0_1264
	s_waitcnt lgkmcnt(0)
	v_add_f32_e32 v96, v96, v97
	v_mul_f32_e32 v96, 0x4b800000, v96
	v_trunc_f32_e32 v96, v96
	v_mul_f32_e32 v97, 0x2f800000, v96
	v_floor_f32_e32 v97, v97
	v_fmac_f32_e32 v96, 0xcf800000, v97
	v_cvt_u32_f32_e32 v96, v96
	v_cvt_u32_f32_e32 v97, v97
	v_lshl_add_u64 v[98:99], v[112:113], 3, s[18:19]
	global_atomic_add_x2 v[98:99], v[96:97], off
; __device__ __forceinline__ unsigned cvtpk(float lo, float hi) { f32x2_t v = {lo, hi}; bf16x2_t b = __builtin_convertvector(v, bf16x2_t); return __builtin_bit_cast(unsigned, b); }
;     __device__ __forceinline__ void operator()(const Acc& acc, const Unit& u, int wr, int wc, int fr, int fq) const {
;     ...
;             for (int m = 0; m < 4; ++m) { const int row = row0 + ai * HALF + m * 16; float* rp = X + (size_t)row * DM + col0; const float* ip = Xin + (size_t)row * DM + col0; bf16_t* bp = XB + (size_t)row * DM + col0; float part = 0.f;
; #pragma unroll
;                 for (int bj = 0; bj < 2; ++bj) { f32x4* p = (f32x4*)(rp + bj * HALF); const f32x4* q = (const f32x4*)(ip + bj * HALF); f32x4 a = q[0], b = q[1]; a += acc[ai][bj][m][0] * scale; b += acc[ai][bj][m][1] * scale; p[0] = a; p[1] = b;
;                     *(u32x4*)(bp + bj * HALF) = (u32x4){cvtpk(a[0], a[1]), cvtpk(a[2], a[3]), cvtpk(b[0], b[1]), cvtpk(b[2], b[3])};
;                     part += (a[0] * a[0] + a[1] * a[1]) + (a[2] * a[2] + a[3] * a[3]) + (b[0] * b[0] + b[1] * b[1]) + (b[2] * b[2] + b[3] * b[3]); }
;                 part += __shfl_xor(part, 16); part += __shfl_xor(part, 32);
;                 if (fq == 0) __hip_atomic_fetch_add(SS + row, (u64)(part * SSF), __ATOMIC_RELAXED, __HIP_MEMORY_SCOPE_AGENT); }
.LBB0_1264:
	s_or_b64 exec, exec, s[16:17]
	v_or_b32_e32 v96, 32, v140
	s_waitcnt lgkmcnt(0)
	v_ashrrev_i32_e32 v97, 31, v96
	v_lshlrev_b64 v[98:99], 12, v[96:97]
	v_lshl_add_u64 v[98:99], s[48:49], 0, v[98:99]
	v_lshl_add_u64 v[106:107], v[138:139], 2, v[98:99]
	global_load_dwordx4 v[98:101], v[106:107], off nt
	global_load_dwordx4 v[102:105], v[106:107], off offset:16 nt
	v_lshlrev_b64 v[108:109], 11, v[96:97]
	v_lshl_add_u64 v[108:109], s[14:15], 0, v[108:109]
	v_lshl_add_u64 v[108:109], v[138:139], 1, v[108:109]
	s_waitcnt vmcnt(1)
	v_pk_fma_f32 v[94:95], v[94:95], 0.5, v[100:101] op_sel_hi:[1,0,1]
	v_pk_fma_f32 v[92:93], v[92:93], 0.5, v[98:99] op_sel_hi:[1,0,1]
	s_waitcnt vmcnt(0)
	v_pk_fma_f32 v[90:91], v[90:91], 0.5, v[104:105] op_sel_hi:[1,0,1]
	v_pk_fma_f32 v[88:89], v[88:89], 0.5, v[102:103] op_sel_hi:[1,0,1]
	v_cvt_pk_bf16_f32 v98, v92, v93
	v_cvt_pk_bf16_f32 v99, v94, v95
	v_cvt_pk_bf16_f32 v100, v88, v89
	v_cvt_pk_bf16_f32 v101, v90, v91
	global_store_dwordx4 v[106:107], v[92:95], off
	global_store_dwordx4 v[106:107], v[88:91], off offset:16
	global_store_dwordx4 v[108:109], v[98:101], off
	global_load_dwordx4 v[98:101], v[106:107], off offset:512 nt
	s_nop 0
	global_load_dwordx4 v[102:105], v[106:107], off offset:528 nt
	v_mul_f32_e32 v93, v93, v93
	v_mul_f32_e32 v95, v95, v95
	v_mul_f32_e32 v89, v89, v89
	v_fmac_f32_e32 v93, v92, v92
	v_fmac_f32_e32 v95, v94, v94
	v_mul_f32_e32 v91, v91, v91
	v_fmac_f32_e32 v89, v88, v88
	v_add_f32_e32 v88, v93, v95
	v_fmac_f32_e32 v91, v90, v90
	v_add_f32_e32 v88, v89, v88
	v_add_f32_e32 v92, v91, v88
	s_waitcnt vmcnt(1)
	v_pk_fma_f32 v[86:87], v[86:87], 0.5, v[100:101] op_sel_hi:[1,0,1]
	v_pk_fma_f32 v[84:85], v[84:85], 0.5, v[98:99] op_sel_hi:[1,0,1]
	s_waitcnt vmcnt(0)
	v_pk_fma_f32 v[88:89], v[80:81], 0.5, v[102:103] op_sel_hi:[1,0,1]
	v_mul_f32_e32 v80, v85, v85
	v_mul_f32_e32 v81, v87, v87
	v_pk_fma_f32 v[90:91], v[82:83], 0.5, v[104:105] op_sel_hi:[1,0,1]
	v_mul_f32_e32 v82, v89, v89
	v_fmac_f32_e32 v80, v84, v84
	v_fmac_f32_e32 v81, v86, v86
	v_mul_f32_e32 v83, v91, v91
	v_fmac_f32_e32 v82, v88, v88
	v_add_f32_e32 v80, v80, v81
	v_add_f32_e32 v80, v82, v80
	v_fmac_f32_e32 v83, v90, v90
	v_add_f32_e32 v80, v83, v80
	v_add_f32_e32 v80, v92, v80
	ds_bpermute_b32 v81, v120, v80
	global_store_dwordx4 v[106:107], v[84:87], off offset:512
	global_store_dwordx4 v[106:107], v[88:91], off offset:528
	v_cvt_pk_bf16_f32 v82, v84, v85
	v_cvt_pk_bf16_f32 v83, v86, v87
	v_cvt_pk_bf16_f32 v84, v88, v89
	s_waitcnt lgkmcnt(0)
	v_add_f32_e32 v80, v80, v81
	ds_bpermute_b32 v81, v114, v80
	v_cvt_pk_bf16_f32 v85, v90, v91
	global_store_dwordx4 v[108:109], v[82:85], off offset:256
	s_and_saveexec_b64 s[16:17], s[40:41]
	s_cbranch_execz .LBB0_1266
	s_waitcnt lgkmcnt(0)
	v_add_f32_e32 v80, v80, v81
	v_mul_f32_e32 v80, 0x4b800000, v80
	v_trunc_f32_e32 v80, v80
	v_mul_f32_e32 v81, 0x2f800000, v80
	v_floor_f32_e32 v81, v81
	v_fmac_f32_e32 v80, 0xcf800000, v81
	v_cvt_u32_f32_e32 v80, v80
	v_cvt_u32_f32_e32 v81, v81
	v_lshl_add_u64 v[82:83], v[96:97], 3, s[18:19]
	global_atomic_add_x2 v[82:83], v[80:81], off
.LBB0_1266:
	s_or_b64 exec, exec, s[16:17]
	v_or_b32_e32 v80, 48, v140
	s_waitcnt lgkmcnt(0)
	v_ashrrev_i32_e32 v81, 31, v80
	v_lshlrev_b64 v[82:83], 12, v[80:81]
	v_lshl_add_u64 v[82:83], s[48:49], 0, v[82:83]
	v_lshl_add_u64 v[90:91], v[138:139], 2, v[82:83]
	global_load_dwordx4 v[82:85], v[90:91], off nt
	global_load_dwordx4 v[86:89], v[90:91], off offset:16 nt
	v_lshlrev_b64 v[92:93], 11, v[80:81]
	v_lshl_add_u64 v[92:93], s[14:15], 0, v[92:93]
	v_lshl_add_u64 v[92:93], v[138:139], 1, v[92:93]
	s_waitcnt vmcnt(1)
	v_pk_fma_f32 v[78:79], v[78:79], 0.5, v[84:85] op_sel_hi:[1,0,1]
	v_pk_fma_f32 v[76:77], v[76:77], 0.5, v[82:83] op_sel_hi:[1,0,1]
	s_waitcnt vmcnt(0)
	v_pk_fma_f32 v[74:75], v[74:75], 0.5, v[88:89] op_sel_hi:[1,0,1]
	v_pk_fma_f32 v[72:73], v[72:73], 0.5, v[86:87] op_sel_hi:[1,0,1]
	v_cvt_pk_bf16_f32 v82, v76, v77
	v_cvt_pk_bf16_f32 v83, v78, v79
	v_cvt_pk_bf16_f32 v84, v72, v73
	v_cvt_pk_bf16_f32 v85, v74, v75
	global_store_dwordx4 v[90:91], v[76:79], off
	global_store_dwordx4 v[90:91], v[72:75], off offset:16
	global_store_dwordx4 v[92:93], v[82:85], off
	global_load_dwordx4 v[82:85], v[90:91], off offset:512 nt
	s_nop 0
	global_load_dwordx4 v[86:89], v[90:91], off offset:528 nt
	v_mul_f32_e32 v77, v77, v77
	v_mul_f32_e32 v79, v79, v79
	v_mul_f32_e32 v73, v73, v73
	v_fmac_f32_e32 v77, v76, v76
	v_fmac_f32_e32 v79, v78, v78
	v_mul_f32_e32 v75, v75, v75
	v_fmac_f32_e32 v73, v72, v72
	v_add_f32_e32 v72, v77, v79
	v_fmac_f32_e32 v75, v74, v74
	v_add_f32_e32 v72, v73, v72
	v_add_f32_e32 v76, v75, v72
	s_waitcnt vmcnt(1)
	v_pk_fma_f32 v[70:71], v[70:71], 0.5, v[84:85] op_sel_hi:[1,0,1]
	v_pk_fma_f32 v[68:69], v[68:69], 0.5, v[82:83] op_sel_hi:[1,0,1]
	s_waitcnt vmcnt(0)
	v_pk_fma_f32 v[72:73], v[64:65], 0.5, v[86:87] op_sel_hi:[1,0,1]
	v_mul_f32_e32 v64, v69, v69
	v_mul_f32_e32 v65, v71, v71
	v_pk_fma_f32 v[74:75], v[66:67], 0.5, v[88:89] op_sel_hi:[1,0,1]
	v_mul_f32_e32 v66, v73, v73
	v_fmac_f32_e32 v64, v68, v68
	v_fmac_f32_e32 v65, v70, v70
	v_mul_f32_e32 v67, v75, v75
	v_fmac_f32_e32 v66, v72, v72
	v_add_f32_e32 v64, v64, v65
	v_add_f32_e32 v64, v66, v64
	v_fmac_f32_e32 v67, v74, v74
	v_add_f32_e32 v64, v67, v64
	v_add_f32_e32 v64, v76, v64
	ds_bpermute_b32 v65, v120, v64
	global_store_dwordx4 v[90:91], v[68:71], off offset:512
	global_store_dwordx4 v[90:91], v[72:75], off offset:528
	v_cvt_pk_bf16_f32 v66, v68, v69
	v_cvt_pk_bf16_f32 v67, v70, v71
	v_cvt_pk_bf16_f32 v68, v72, v73
	s_waitcnt lgkmcnt(0)
	v_add_f32_e32 v64, v64, v65
	ds_bpermute_b32 v65, v114, v64
	v_cvt_pk_bf16_f32 v69, v74, v75
	global_store_dwordx4 v[92:93], v[66:69], off offset:256
	s_and_saveexec_b64 s[16:17], s[40:41]
	s_cbranch_execz .LBB0_1268
	s_waitcnt lgkmcnt(0)
	v_add_f32_e32 v64, v64, v65
	v_mul_f32_e32 v64, 0x4b800000, v64
	v_trunc_f32_e32 v64, v64
	v_mul_f32_e32 v65, 0x2f800000, v64
	v_floor_f32_e32 v65, v65
	v_fmac_f32_e32 v64, 0xcf800000, v65
	v_cvt_u32_f32_e32 v64, v64
	v_cvt_u32_f32_e32 v65, v65
	v_lshl_add_u64 v[66:67], v[80:81], 3, s[18:19]
	global_atomic_add_x2 v[66:67], v[64:65], off
; __device__ __forceinline__ unsigned cvtpk(float lo, float hi) { f32x2_t v = {lo, hi}; bf16x2_t b = __builtin_convertvector(v, bf16x2_t); return __builtin_bit_cast(unsigned, b); }
;     __device__ __forceinline__ void operator()(const Acc& acc, const Unit& u, int wr, int wc, int fr, int fq) const {
;     ...
;             for (int m = 0; m < 4; ++m) { const int row = row0 + ai * HALF + m * 16; float* rp = X + (size_t)row * DM + col0; const float* ip = Xin + (size_t)row * DM + col0; bf16_t* bp = XB + (size_t)row * DM + col0; float part = 0.f;
; #pragma unroll
;                 for (int bj = 0; bj < 2; ++bj) { f32x4* p = (f32x4*)(rp + bj * HALF); const f32x4* q = (const f32x4*)(ip + bj * HALF); f32x4 a = q[0], b = q[1]; a += acc[ai][bj][m][0] * scale; b += acc[ai][bj][m][1] * scale; p[0] = a; p[1] = b;
;                     *(u32x4*)(bp + bj * HALF) = (u32x4){cvtpk(a[0], a[1]), cvtpk(a[2], a[3]), cvtpk(b[0], b[1]), cvtpk(b[2], b[3])};
;                     part += (a[0] * a[0] + a[1] * a[1]) + (a[2] * a[2] + a[3] * a[3]) + (b[0] * b[0] + b[1] * b[1]) + (b[2] * b[2] + b[3] * b[3]); }
;                 part += __shfl_xor(part, 16); part += __shfl_xor(part, 32);
;                 if (fq == 0) __hip_atomic_fetch_add(SS + row, (u64)(part * SSF), __ATOMIC_RELAXED, __HIP_MEMORY_SCOPE_AGENT); }
.LBB0_1268:
	s_or_b64 exec, exec, s[16:17]
	v_add_u32_e32 v64, 0x80, v140
	s_waitcnt lgkmcnt(0)
	v_ashrrev_i32_e32 v65, 31, v64
	v_lshlrev_b64 v[66:67], 12, v[64:65]
	v_lshl_add_u64 v[66:67], s[48:49], 0, v[66:67]
	v_lshl_add_u64 v[74:75], v[138:139], 2, v[66:67]
	global_load_dwordx4 v[66:69], v[74:75], off nt
	global_load_dwordx4 v[70:73], v[74:75], off offset:16 nt
	v_lshlrev_b64 v[76:77], 11, v[64:65]
	v_lshl_add_u64 v[76:77], s[14:15], 0, v[76:77]
	v_lshl_add_u64 v[76:77], v[138:139], 1, v[76:77]
	s_waitcnt vmcnt(1)
	v_pk_fma_f32 v[62:63], v[62:63], 0.5, v[68:69] op_sel_hi:[1,0,1]
	v_pk_fma_f32 v[60:61], v[60:61], 0.5, v[66:67] op_sel_hi:[1,0,1]
	s_waitcnt vmcnt(0)
	v_pk_fma_f32 v[58:59], v[58:59], 0.5, v[72:73] op_sel_hi:[1,0,1]
	v_pk_fma_f32 v[56:57], v[56:57], 0.5, v[70:71] op_sel_hi:[1,0,1]
	v_cvt_pk_bf16_f32 v66, v60, v61
	v_cvt_pk_bf16_f32 v67, v62, v63
	v_cvt_pk_bf16_f32 v68, v56, v57
	v_cvt_pk_bf16_f32 v69, v58, v59
	global_store_dwordx4 v[74:75], v[60:63], off
	global_store_dwordx4 v[74:75], v[56:59], off offset:16
	global_store_dwordx4 v[76:77], v[66:69], off
	global_load_dwordx4 v[66:69], v[74:75], off offset:512 nt
	s_nop 0
	global_load_dwordx4 v[70:73], v[74:75], off offset:528 nt
	v_mul_f32_e32 v61, v61, v61
	v_mul_f32_e32 v63, v63, v63
	v_mul_f32_e32 v57, v57, v57
	v_fmac_f32_e32 v61, v60, v60
	v_fmac_f32_e32 v63, v62, v62
	v_mul_f32_e32 v59, v59, v59
	v_fmac_f32_e32 v57, v56, v56
	v_add_f32_e32 v56, v61, v63
	v_fmac_f32_e32 v59, v58, v58
	v_add_f32_e32 v56, v57, v56
	v_add_f32_e32 v60, v59, v56
	s_waitcnt vmcnt(1)
	v_pk_fma_f32 v[54:55], v[54:55], 0.5, v[68:69] op_sel_hi:[1,0,1]
	v_pk_fma_f32 v[52:53], v[52:53], 0.5, v[66:67] op_sel_hi:[1,0,1]
	s_waitcnt vmcnt(0)
	v_pk_fma_f32 v[56:57], v[48:49], 0.5, v[70:71] op_sel_hi:[1,0,1]
	v_mul_f32_e32 v48, v53, v53
	v_mul_f32_e32 v49, v55, v55
	v_pk_fma_f32 v[58:59], v[50:51], 0.5, v[72:73] op_sel_hi:[1,0,1]
	v_mul_f32_e32 v50, v57, v57
	v_fmac_f32_e32 v48, v52, v52
	v_fmac_f32_e32 v49, v54, v54
	v_mul_f32_e32 v51, v59, v59
	v_fmac_f32_e32 v50, v56, v56
	v_add_f32_e32 v48, v48, v49
	v_add_f32_e32 v48, v50, v48
	v_fmac_f32_e32 v51, v58, v58
	v_add_f32_e32 v48, v51, v48
	v_add_f32_e32 v48, v60, v48
	ds_bpermute_b32 v49, v120, v48
	global_store_dwordx4 v[74:75], v[52:55], off offset:512
	global_store_dwordx4 v[74:75], v[56:59], off offset:528
	v_cvt_pk_bf16_f32 v50, v52, v53
	v_cvt_pk_bf16_f32 v51, v54, v55
	v_cvt_pk_bf16_f32 v52, v56, v57
	s_waitcnt lgkmcnt(0)
	v_add_f32_e32 v48, v48, v49
	ds_bpermute_b32 v49, v114, v48
	v_cvt_pk_bf16_f32 v53, v58, v59
	global_store_dwordx4 v[76:77], v[50:53], off offset:256
	s_and_saveexec_b64 s[16:17], s[40:41]
	s_cbranch_execz .LBB0_1270
	s_waitcnt lgkmcnt(0)
	v_add_f32_e32 v48, v48, v49
	v_mul_f32_e32 v48, 0x4b800000, v48
	v_trunc_f32_e32 v48, v48
	v_mul_f32_e32 v49, 0x2f800000, v48
	v_floor_f32_e32 v49, v49
	v_fmac_f32_e32 v48, 0xcf800000, v49
	v_cvt_u32_f32_e32 v48, v48
	v_cvt_u32_f32_e32 v49, v49
	v_lshl_add_u64 v[50:51], v[64:65], 3, s[18:19]
	global_atomic_add_x2 v[50:51], v[48:49], off
.LBB0_1270:
	s_or_b64 exec, exec, s[16:17]
	v_add_u32_e32 v48, 0x90, v140
	s_waitcnt lgkmcnt(0)
	v_ashrrev_i32_e32 v49, 31, v48
	v_lshlrev_b64 v[50:51], 12, v[48:49]
	v_lshl_add_u64 v[50:51], s[48:49], 0, v[50:51]
	v_lshl_add_u64 v[58:59], v[138:139], 2, v[50:51]
	global_load_dwordx4 v[50:53], v[58:59], off nt
	global_load_dwordx4 v[54:57], v[58:59], off offset:16 nt
	v_lshlrev_b64 v[60:61], 11, v[48:49]
	v_lshl_add_u64 v[60:61], s[14:15], 0, v[60:61]
	v_lshl_add_u64 v[60:61], v[138:139], 1, v[60:61]
	s_waitcnt vmcnt(1)
	v_pk_fma_f32 v[46:47], v[46:47], 0.5, v[52:53] op_sel_hi:[1,0,1]
	v_pk_fma_f32 v[44:45], v[44:45], 0.5, v[50:51] op_sel_hi:[1,0,1]
	s_waitcnt vmcnt(0)
	v_pk_fma_f32 v[42:43], v[42:43], 0.5, v[56:57] op_sel_hi:[1,0,1]
	v_pk_fma_f32 v[40:41], v[40:41], 0.5, v[54:55] op_sel_hi:[1,0,1]
	v_cvt_pk_bf16_f32 v50, v44, v45
	v_cvt_pk_bf16_f32 v51, v46, v47
	v_cvt_pk_bf16_f32 v52, v40, v41
	v_cvt_pk_bf16_f32 v53, v42, v43
	global_store_dwordx4 v[58:59], v[44:47], off
	global_store_dwordx4 v[58:59], v[40:43], off offset:16
	global_store_dwordx4 v[60:61], v[50:53], off
	global_load_dwordx4 v[50:53], v[58:59], off offset:512 nt
	s_nop 0
	global_load_dwordx4 v[54:57], v[58:59], off offset:528 nt
	v_mul_f32_e32 v45, v45, v45
	v_mul_f32_e32 v47, v47, v47
	v_mul_f32_e32 v41, v41, v41
	v_fmac_f32_e32 v45, v44, v44
	v_fmac_f32_e32 v47, v46, v46
	v_mul_f32_e32 v43, v43, v43
	v_fmac_f32_e32 v41, v40, v40
	v_add_f32_e32 v40, v45, v47
	v_fmac_f32_e32 v43, v42, v42
	v_add_f32_e32 v40, v41, v40
	v_add_f32_e32 v44, v43, v40
	s_waitcnt vmcnt(1)
	v_pk_fma_f32 v[38:39], v[38:39], 0.5, v[52:53] op_sel_hi:[1,0,1]
	v_pk_fma_f32 v[36:37], v[36:37], 0.5, v[50:51] op_sel_hi:[1,0,1]
	s_waitcnt vmcnt(0)
	v_pk_fma_f32 v[40:41], v[32:33], 0.5, v[54:55] op_sel_hi:[1,0,1]
	v_mul_f32_e32 v32, v37, v37
	v_mul_f32_e32 v33, v39, v39
	v_pk_fma_f32 v[42:43], v[34:35], 0.5, v[56:57] op_sel_hi:[1,0,1]
	v_mul_f32_e32 v34, v41, v41
	v_fmac_f32_e32 v32, v36, v36
	v_fmac_f32_e32 v33, v38, v38
	v_mul_f32_e32 v35, v43, v43
	v_fmac_f32_e32 v34, v40, v40
	v_add_f32_e32 v32, v32, v33
	v_add_f32_e32 v32, v34, v32
	v_fmac_f32_e32 v35, v42, v42
	v_add_f32_e32 v32, v35, v32
	v_add_f32_e32 v32, v44, v32
	ds_bpermute_b32 v33, v120, v32
	global_store_dwordx4 v[58:59], v[36:39], off offset:512
	global_store_dwordx4 v[58:59], v[40:43], off offset:528
	v_cvt_pk_bf16_f32 v34, v36, v37
	v_cvt_pk_bf16_f32 v35, v38, v39
	v_cvt_pk_bf16_f32 v36, v40, v41
	s_waitcnt lgkmcnt(0)
	v_add_f32_e32 v32, v32, v33
	ds_bpermute_b32 v33, v114, v32
	v_cvt_pk_bf16_f32 v37, v42, v43
	global_store_dwordx4 v[60:61], v[34:37], off offset:256
	s_and_saveexec_b64 s[16:17], s[40:41]
	s_cbranch_execz .LBB0_1272
	s_waitcnt lgkmcnt(0)
	v_add_f32_e32 v32, v32, v33
	v_mul_f32_e32 v32, 0x4b800000, v32
	v_trunc_f32_e32 v32, v32
	v_mul_f32_e32 v33, 0x2f800000, v32
	v_floor_f32_e32 v33, v33
	v_fmac_f32_e32 v32, 0xcf800000, v33
	v_cvt_u32_f32_e32 v32, v32
	v_cvt_u32_f32_e32 v33, v33
	v_lshl_add_u64 v[34:35], v[48:49], 3, s[18:19]
	global_atomic_add_x2 v[34:35], v[32:33], off
; __device__ __forceinline__ unsigned cvtpk(float lo, float hi) { f32x2_t v = {lo, hi}; bf16x2_t b = __builtin_convertvector(v, bf16x2_t); return __builtin_bit_cast(unsigned, b); }
;     __device__ __forceinline__ void operator()(const Acc& acc, const Unit& u, int wr, int wc, int fr, int fq) const {
;     ...
;             for (int m = 0; m < 4; ++m) { const int row = row0 + ai * HALF + m * 16; float* rp = X + (size_t)row * DM + col0; const float* ip = Xin + (size_t)row * DM + col0; bf16_t* bp = XB + (size_t)row * DM + col0; float part = 0.f;
; #pragma unroll
;                 for (int bj = 0; bj < 2; ++bj) { f32x4* p = (f32x4*)(rp + bj * HALF); const f32x4* q = (const f32x4*)(ip + bj * HALF); f32x4 a = q[0], b = q[1]; a += acc[ai][bj][m][0] * scale; b += acc[ai][bj][m][1] * scale; p[0] = a; p[1] = b;
;                     *(u32x4*)(bp + bj * HALF) = (u32x4){cvtpk(a[0], a[1]), cvtpk(a[2], a[3]), cvtpk(b[0], b[1]), cvtpk(b[2], b[3])};
;                     part += (a[0] * a[0] + a[1] * a[1]) + (a[2] * a[2] + a[3] * a[3]) + (b[0] * b[0] + b[1] * b[1]) + (b[2] * b[2] + b[3] * b[3]); }
;                 part += __shfl_xor(part, 16); part += __shfl_xor(part, 32);
;                 if (fq == 0) __hip_atomic_fetch_add(SS + row, (u64)(part * SSF), __ATOMIC_RELAXED, __HIP_MEMORY_SCOPE_AGENT); }
.LBB0_1272:
	s_or_b64 exec, exec, s[16:17]
	v_add_u32_e32 v32, 0xa0, v140
	s_waitcnt lgkmcnt(0)
	v_ashrrev_i32_e32 v33, 31, v32
	v_lshlrev_b64 v[34:35], 12, v[32:33]
	v_lshl_add_u64 v[34:35], s[48:49], 0, v[34:35]
	v_lshl_add_u64 v[42:43], v[138:139], 2, v[34:35]
	global_load_dwordx4 v[34:37], v[42:43], off nt
	global_load_dwordx4 v[38:41], v[42:43], off offset:16 nt
	v_lshlrev_b64 v[44:45], 11, v[32:33]
	v_lshl_add_u64 v[44:45], s[14:15], 0, v[44:45]
	v_lshl_add_u64 v[44:45], v[138:139], 1, v[44:45]
	s_waitcnt vmcnt(1)
	v_pk_fma_f32 v[30:31], v[30:31], 0.5, v[36:37] op_sel_hi:[1,0,1]
	v_pk_fma_f32 v[28:29], v[28:29], 0.5, v[34:35] op_sel_hi:[1,0,1]
	s_waitcnt vmcnt(0)
	v_pk_fma_f32 v[26:27], v[26:27], 0.5, v[40:41] op_sel_hi:[1,0,1]
	v_pk_fma_f32 v[24:25], v[24:25], 0.5, v[38:39] op_sel_hi:[1,0,1]
	v_cvt_pk_bf16_f32 v34, v28, v29
	v_cvt_pk_bf16_f32 v35, v30, v31
	v_cvt_pk_bf16_f32 v36, v24, v25
	v_cvt_pk_bf16_f32 v37, v26, v27
	global_store_dwordx4 v[42:43], v[28:31], off
	global_store_dwordx4 v[42:43], v[24:27], off offset:16
	global_store_dwordx4 v[44:45], v[34:37], off
	global_load_dwordx4 v[34:37], v[42:43], off offset:512 nt
	s_nop 0
	global_load_dwordx4 v[38:41], v[42:43], off offset:528 nt
	v_mul_f32_e32 v29, v29, v29
	v_mul_f32_e32 v31, v31, v31
	v_mul_f32_e32 v25, v25, v25
	v_fmac_f32_e32 v29, v28, v28
	v_fmac_f32_e32 v31, v30, v30
	v_mul_f32_e32 v27, v27, v27
	v_fmac_f32_e32 v25, v24, v24
	v_add_f32_e32 v24, v29, v31
	v_fmac_f32_e32 v27, v26, v26
	v_add_f32_e32 v24, v25, v24
	v_add_f32_e32 v28, v27, v24
	s_waitcnt vmcnt(1)
	v_pk_fma_f32 v[22:23], v[22:23], 0.5, v[36:37] op_sel_hi:[1,0,1]
	v_pk_fma_f32 v[20:21], v[20:21], 0.5, v[34:35] op_sel_hi:[1,0,1]
	s_waitcnt vmcnt(0)
	v_pk_fma_f32 v[24:25], v[16:17], 0.5, v[38:39] op_sel_hi:[1,0,1]
	v_mul_f32_e32 v16, v21, v21
	v_mul_f32_e32 v17, v23, v23
	v_pk_fma_f32 v[26:27], v[18:19], 0.5, v[40:41] op_sel_hi:[1,0,1]
	v_mul_f32_e32 v18, v25, v25
	v_fmac_f32_e32 v16, v20, v20
	v_fmac_f32_e32 v17, v22, v22
	v_mul_f32_e32 v19, v27, v27
	v_fmac_f32_e32 v18, v24, v24
	v_add_f32_e32 v16, v16, v17
	v_add_f32_e32 v16, v18, v16
	v_fmac_f32_e32 v19, v26, v26
	v_add_f32_e32 v16, v19, v16
	v_add_f32_e32 v16, v28, v16
	ds_bpermute_b32 v17, v120, v16
	global_store_dwordx4 v[42:43], v[20:23], off offset:512
	global_store_dwordx4 v[42:43], v[24:27], off offset:528
	v_cvt_pk_bf16_f32 v18, v20, v21
	v_cvt_pk_bf16_f32 v19, v22, v23
	v_cvt_pk_bf16_f32 v20, v24, v25
	s_waitcnt lgkmcnt(0)
	v_add_f32_e32 v16, v16, v17
	ds_bpermute_b32 v17, v114, v16
	v_cvt_pk_bf16_f32 v21, v26, v27
	global_store_dwordx4 v[44:45], v[18:21], off offset:256
	s_and_saveexec_b64 s[16:17], s[40:41]
	s_cbranch_execz .LBB0_1274
	s_waitcnt lgkmcnt(0)
	v_add_f32_e32 v16, v16, v17
	v_mul_f32_e32 v16, 0x4b800000, v16
	v_trunc_f32_e32 v16, v16
	v_mul_f32_e32 v17, 0x2f800000, v16
	v_floor_f32_e32 v17, v17
	v_fmac_f32_e32 v16, 0xcf800000, v17
	v_cvt_u32_f32_e32 v16, v16
	v_cvt_u32_f32_e32 v17, v17
	v_lshl_add_u64 v[18:19], v[32:33], 3, s[18:19]
	global_atomic_add_x2 v[18:19], v[16:17], off
.LBB0_1274:
	s_or_b64 exec, exec, s[16:17]
	v_add_u32_e32 v16, 0xb0, v140
	s_waitcnt lgkmcnt(0)
	v_ashrrev_i32_e32 v17, 31, v16
	v_lshlrev_b64 v[18:19], 12, v[16:17]
	v_lshl_add_u64 v[18:19], s[48:49], 0, v[18:19]
	v_lshl_add_u64 v[26:27], v[138:139], 2, v[18:19]
	v_lshlrev_b64 v[18:19], 11, v[16:17]
	v_lshl_add_u64 v[18:19], s[14:15], 0, v[18:19]
	v_lshl_add_u64 v[28:29], v[138:139], 1, v[18:19]
	global_load_dwordx4 v[18:21], v[26:27], off offset:16 nt
	global_load_dwordx4 v[22:25], v[26:27], off nt
	s_waitcnt vmcnt(1)
	v_pk_fma_f32 v[10:11], v[10:11], 0.5, v[20:21] op_sel_hi:[1,0,1]
	s_waitcnt vmcnt(0)
	v_pk_fma_f32 v[14:15], v[14:15], 0.5, v[24:25] op_sel_hi:[1,0,1]
	v_pk_fma_f32 v[12:13], v[12:13], 0.5, v[22:23] op_sel_hi:[1,0,1]
	v_pk_fma_f32 v[8:9], v[8:9], 0.5, v[18:19] op_sel_hi:[1,0,1]
	global_store_dwordx4 v[26:27], v[12:15], off
	global_store_dwordx4 v[26:27], v[8:11], off offset:16
	v_cvt_pk_bf16_f32 v18, v12, v13
	v_mul_f32_e32 v13, v13, v13
	v_fmac_f32_e32 v13, v12, v12
	v_mul_f32_e32 v12, v15, v15
	v_cvt_pk_bf16_f32 v20, v8, v9
	v_fmac_f32_e32 v12, v14, v14
	v_mul_f32_e32 v9, v9, v9
	v_add_f32_e32 v12, v13, v12
	v_fmac_f32_e32 v9, v8, v8
	v_cvt_pk_bf16_f32 v19, v14, v15
	v_cvt_pk_bf16_f32 v21, v10, v11
	v_add_f32_e32 v8, v9, v12
	v_mul_f32_e32 v9, v11, v11
	global_store_dwordx4 v[28:29], v[18:21], off
	v_fmac_f32_e32 v9, v10, v10
	s_nop 0
	v_add_f32_e32 v18, v9, v8
	global_load_dwordx4 v[8:11], v[26:27], off offset:528 nt
	global_load_dwordx4 v[12:15], v[26:27], off offset:512 nt
	s_waitcnt vmcnt(1)
	v_pk_fma_f32 v[2:3], v[2:3], 0.5, v[10:11] op_sel_hi:[1,0,1]
	s_waitcnt vmcnt(0)
	v_pk_fma_f32 v[6:7], v[6:7], 0.5, v[14:15] op_sel_hi:[1,0,1]
	v_pk_fma_f32 v[4:5], v[4:5], 0.5, v[12:13] op_sel_hi:[1,0,1]
	v_pk_fma_f32 v[0:1], v[0:1], 0.5, v[8:9] op_sel_hi:[1,0,1]
	global_store_dwordx4 v[26:27], v[4:7], off offset:512
	global_store_dwordx4 v[26:27], v[0:3], off offset:528
	v_cvt_pk_bf16_f32 v8, v4, v5
	v_mul_f32_e32 v5, v5, v5
	v_fmac_f32_e32 v5, v4, v4
	v_mul_f32_e32 v4, v7, v7
	v_cvt_pk_bf16_f32 v10, v0, v1
	v_fmac_f32_e32 v4, v6, v6
	v_mul_f32_e32 v1, v1, v1
	v_add_f32_e32 v4, v5, v4
	v_fmac_f32_e32 v1, v0, v0
	v_add_f32_e32 v0, v1, v4
	v_mul_f32_e32 v1, v3, v3
	v_fmac_f32_e32 v1, v2, v2
	v_add_f32_e32 v0, v1, v0
	v_add_f32_e32 v0, v18, v0
	ds_bpermute_b32 v1, v120, v0
	v_cvt_pk_bf16_f32 v9, v6, v7
	v_cvt_pk_bf16_f32 v11, v2, v3
	global_store_dwordx4 v[28:29], v[8:11], off offset:256
	s_waitcnt lgkmcnt(0)
	v_add_f32_e32 v0, v0, v1
	ds_bpermute_b32 v1, v114, v0
	s_and_saveexec_b64 s[16:17], s[40:41]
	s_cbranch_execz .LBB0_1276
	s_waitcnt lgkmcnt(0)
	v_add_f32_e32 v0, v0, v1
	v_mul_f32_e32 v0, 0x4b800000, v0
	v_trunc_f32_e32 v0, v0
	v_mul_f32_e32 v1, 0x2f800000, v0
	v_floor_f32_e32 v1, v1
	v_fmac_f32_e32 v0, 0xcf800000, v1
	v_cvt_u32_f32_e32 v0, v0
	v_cvt_u32_f32_e32 v1, v1
	v_lshl_add_u64 v[2:3], v[16:17], 3, s[18:19]
	global_atomic_add_x2 v[2:3], v[0:1], off
